# hand-written sample-row attention: K/V window staged once per WG in LDS with coalesced loads (was lane-strided f32 K reads), q/p broadcast via LDS
# speedup vs baseline: 1.0235x; 1.0140x over previous
.LBB0_126:
	s_mov_b64 s[54:55], exec
	s_waitcnt vmcnt(0) lgkmcnt(0)
	s_barrier
	s_load_dwordx2 s[38:39], s[80:81], 0x20
	s_load_dwordx2 s[40:41], s[80:81], 0x28
	s_load_dwordx2 s[56:57], s[80:81], 0xd0
	s_lshr_b32 s45, s90, 1
	s_and_b32 s46, s90, 1
	v_readfirstlane_b32 s47, v204
	v_and_b32_e32 v0, 15, v204
	v_lshrrev_b32_e32 v2, 4, v204
	s_lshr_b32 s47, s47, 6
	s_lshl_b32 s44, s46, 3
	s_add_i32 s44, s44, s47
	s_lshl_b32 s2, s45, 16
	s_lshl_b32 s3, s46, 8
	s_add_i32 s2, s2, s3
	v_lshlrev_b32_e32 v3, 9, v2
	v_lshl_add_u32 v3, v0, 4, v3
	v_add_u32_e32 v3, s2, v3
	v_add_u32_e32 v4, 0x4000, v3
	v_add_u32_e32 v5, 0x8000, v3
	v_add_u32_e32 v6, 0xc000, v3
	s_waitcnt lgkmcnt(0)
	global_load_dwordx4 v[20:23], v3, s[38:39]
	global_load_dwordx4 v[24:27], v4, s[38:39]
	global_load_dwordx4 v[28:31], v5, s[38:39]
	global_load_dwordx4 v[32:35], v6, s[38:39]
	global_load_dwordx4 v[36:39], v3, s[40:41]
	global_load_dwordx4 v[40:43], v4, s[40:41]
	global_load_dwordx4 v[44:47], v5, s[40:41]
	global_load_dwordx4 v[48:51], v6, s[40:41]
	s_add_u32 s8, s10, 0x13140000
	s_addc_u32 s9, s11, 0
	s_lshl_b32 s2, s45, 11
	s_lshl_b32 s3, s46, 7
	s_add_i32 s2, s2, s3
	s_add_i32 s2, s2, 0x800000
	v_and_b32_e32 v7, 63, v204
	v_bfe_u32 v8, v204, 6, 2
	v_lshrrev_b32_e32 v9, 8, v204
	v_lshlrev_b32_e32 v10, 1, v7
	v_lshl_add_u32 v10, v8, 9, v10
	v_lshl_add_u32 v10, v9, 8, v10
	v_add_u32_e32 v10, s2, v10
	global_load_ushort v52, v10, s[8:9]
	s_add_u32 s42, s10, 0xb580000
	s_addc_u32 s43, s11, 0
	s_lshl_b32 s2, s45, 13
	s_lshl_b32 s3, s44, 7
	s_add_i32 s2, s2, s3
	s_add_i32 s22, s2, 0x2000000
	v_lshl_add_u32 v11, v7, 1, s22
	v_add_u32_e32 v12, 0x1000, v11
	global_load_ushort v56, v11, s[42:43]
	global_load_ushort v57, v11, s[42:43] offset:2048
	global_load_ushort v58, v12, s[42:43]
	global_load_ushort v59, v12, s[42:43] offset:2048
	s_lshl_b32 s2, s44, 2
	s_cmp_gt_u32 s82, 30
	s_cselect_b32 s3, 64, 0
	s_add_i32 s2, s2, s3
	s_load_dword s58, s[56:57], s2
	v_mul_u32_u24_e32 v13, 272, v2
	v_lshl_add_u32 v13, v0, 4, v13
	v_lshlrev_b32_e32 v14, 8, v2
	v_lshl_add_u32 v14, v0, 4, v14
	v_add_u32_e32 v14, 0x9000, v14
	s_waitcnt vmcnt(12)
	ds_write_b128 v13, v[20:23]
	s_waitcnt vmcnt(11)
	ds_write_b128 v13, v[24:27] offset:8704
	s_waitcnt vmcnt(10)
	ds_write_b128 v13, v[28:31] offset:17408
	s_waitcnt vmcnt(9)
	ds_write_b128 v13, v[32:35] offset:26112
	s_waitcnt vmcnt(8)
	ds_write_b128 v14, v[36:39]
	s_waitcnt vmcnt(7)
	ds_write_b128 v14, v[40:43] offset:8192
	s_waitcnt vmcnt(6)
	ds_write_b128 v14, v[44:47] offset:16384
	s_waitcnt vmcnt(5)
	ds_write_b128 v14, v[48:51] offset:24576
	v_mul_u32_u24_e32 v15, 272, v8
	v_add_u32_e32 v15, 34816, v15
	v_lshlrev_b32_e32 v16, 8, v8
	v_add_u32_e32 v16, 69632, v16
	v_cmp_eq_u32_e32 vcc, 0, v9
	s_nop 1
	v_cndmask_b32_e32 v15, v16, v15, vcc
	v_lshl_add_u32 v15, v7, 2, v15
	s_waitcnt vmcnt(4)
	v_lshlrev_b32_e32 v52, 16, v52
	ds_write_b32 v15, v52
	s_lshl_b32 s3, s47, 12
	s_add_i32 s59, s3, 0x12000
	v_lshl_add_u32 v17, v7, 4, s59
	s_waitcnt vmcnt(0)
	v_lshlrev_b32_e32 v56, 16, v56
	v_lshlrev_b32_e32 v57, 16, v57
	v_lshlrev_b32_e32 v58, 16, v58
	v_lshlrev_b32_e32 v59, 16, v59
	ds_write_b128 v17, v[56:59]
	s_waitcnt lgkmcnt(0)
	s_barrier
	v_mul_u32_u24_e32 v19, 272, v7
	v_min_u32_e32 v2, 3, v7
	v_mul_u32_u24_e32 v2, 272, v2
	v_add_u32_e32 v2, 34816, v2
	v_mov_b32_e32 v3, s59
	v_mov_b32_e32 v20, 0
	v_mov_b32_e32 v21, 0
	v_mov_b32_e32 v22, 0
	v_mov_b32_e32 v23, 0
	v_mov_b32_e32 v24, 0
	v_mov_b32_e32 v25, 0
	v_mov_b32_e32 v26, 0
	v_mov_b32_e32 v27, 0
	v_mov_b32_e32 v28, 0
	v_mov_b32_e32 v29, 0
	v_mov_b32_e32 v30, 0
	v_mov_b32_e32 v31, 0
	ds_read_b128 v[32:35], v19 offset:0
	ds_read_b128 v[36:39], v19 offset:17408
	ds_read_b128 v[40:43], v2 offset:0
	ds_read_b128 v[56:59], v3 offset:0
	ds_read_b128 v[60:63], v3 offset:16
	ds_read_b128 v[64:67], v3 offset:32
	ds_read_b128 v[68:71], v3 offset:48
	ds_read_b128 v[44:47], v19 offset:16
	ds_read_b128 v[48:51], v19 offset:17424
	ds_read_b128 v[52:55], v2 offset:16
	s_waitcnt lgkmcnt(7)
	s_waitcnt lgkmcnt(6)
	v_fmac_f32_e32 v20, v56, v32
	v_fmac_f32_e32 v21, v57, v32
	v_fmac_f32_e32 v22, v58, v32
	v_fmac_f32_e32 v23, v59, v32
	v_fmac_f32_e32 v24, v56, v36
	v_fmac_f32_e32 v25, v57, v36
	v_fmac_f32_e32 v26, v58, v36
	v_fmac_f32_e32 v27, v59, v36
	v_fmac_f32_e32 v28, v56, v40
	v_fmac_f32_e32 v29, v57, v40
	v_fmac_f32_e32 v30, v58, v40
	v_fmac_f32_e32 v31, v59, v40
	ds_read_b128 v[56:59], v3 offset:64
	s_waitcnt lgkmcnt(6)
	v_fmac_f32_e32 v20, v60, v33
	v_fmac_f32_e32 v21, v61, v33
	v_fmac_f32_e32 v22, v62, v33
	v_fmac_f32_e32 v23, v63, v33
	v_fmac_f32_e32 v24, v60, v37
	v_fmac_f32_e32 v25, v61, v37
	v_fmac_f32_e32 v26, v62, v37
	v_fmac_f32_e32 v27, v63, v37
	v_fmac_f32_e32 v28, v60, v41
	v_fmac_f32_e32 v29, v61, v41
	v_fmac_f32_e32 v30, v62, v41
	v_fmac_f32_e32 v31, v63, v41
	ds_read_b128 v[60:63], v3 offset:80
	s_waitcnt lgkmcnt(6)
	v_fmac_f32_e32 v20, v64, v34
	v_fmac_f32_e32 v21, v65, v34
	v_fmac_f32_e32 v22, v66, v34
	v_fmac_f32_e32 v23, v67, v34
	v_fmac_f32_e32 v24, v64, v38
	v_fmac_f32_e32 v25, v65, v38
	v_fmac_f32_e32 v26, v66, v38
	v_fmac_f32_e32 v27, v67, v38
	v_fmac_f32_e32 v28, v64, v42
	v_fmac_f32_e32 v29, v65, v42
	v_fmac_f32_e32 v30, v66, v42
	v_fmac_f32_e32 v31, v67, v42
	ds_read_b128 v[64:67], v3 offset:96
	s_waitcnt lgkmcnt(6)
	v_fmac_f32_e32 v20, v68, v35
	v_fmac_f32_e32 v21, v69, v35
	v_fmac_f32_e32 v22, v70, v35
	v_fmac_f32_e32 v23, v71, v35
	v_fmac_f32_e32 v24, v68, v39
	v_fmac_f32_e32 v25, v69, v39
	v_fmac_f32_e32 v26, v70, v39
	v_fmac_f32_e32 v27, v71, v39
	v_fmac_f32_e32 v28, v68, v43
	v_fmac_f32_e32 v29, v69, v43
	v_fmac_f32_e32 v30, v70, v43
	v_fmac_f32_e32 v31, v71, v43
	ds_read_b128 v[68:71], v3 offset:112
	ds_read_b128 v[32:35], v19 offset:32
	ds_read_b128 v[36:39], v19 offset:17440
	ds_read_b128 v[40:43], v2 offset:32
	s_waitcnt lgkmcnt(7)
	s_waitcnt lgkmcnt(6)
	v_fmac_f32_e32 v20, v56, v44
	v_fmac_f32_e32 v21, v57, v44
	v_fmac_f32_e32 v22, v58, v44
	v_fmac_f32_e32 v23, v59, v44
	v_fmac_f32_e32 v24, v56, v48
	v_fmac_f32_e32 v25, v57, v48
	v_fmac_f32_e32 v26, v58, v48
	v_fmac_f32_e32 v27, v59, v48
	v_fmac_f32_e32 v28, v56, v52
	v_fmac_f32_e32 v29, v57, v52
	v_fmac_f32_e32 v30, v58, v52
	v_fmac_f32_e32 v31, v59, v52
	ds_read_b128 v[56:59], v3 offset:128
	s_waitcnt lgkmcnt(6)
	v_fmac_f32_e32 v20, v60, v45
	v_fmac_f32_e32 v21, v61, v45
	v_fmac_f32_e32 v22, v62, v45
	v_fmac_f32_e32 v23, v63, v45
	v_fmac_f32_e32 v24, v60, v49
	v_fmac_f32_e32 v25, v61, v49
	v_fmac_f32_e32 v26, v62, v49
	v_fmac_f32_e32 v27, v63, v49
	v_fmac_f32_e32 v28, v60, v53
	v_fmac_f32_e32 v29, v61, v53
	v_fmac_f32_e32 v30, v62, v53
	v_fmac_f32_e32 v31, v63, v53
	ds_read_b128 v[60:63], v3 offset:144
	s_waitcnt lgkmcnt(6)
	v_fmac_f32_e32 v20, v64, v46
	v_fmac_f32_e32 v21, v65, v46
	v_fmac_f32_e32 v22, v66, v46
	v_fmac_f32_e32 v23, v67, v46
	v_fmac_f32_e32 v24, v64, v50
	v_fmac_f32_e32 v25, v65, v50
	v_fmac_f32_e32 v26, v66, v50
	v_fmac_f32_e32 v27, v67, v50
	v_fmac_f32_e32 v28, v64, v54
	v_fmac_f32_e32 v29, v65, v54
	v_fmac_f32_e32 v30, v66, v54
	v_fmac_f32_e32 v31, v67, v54
	ds_read_b128 v[64:67], v3 offset:160
	s_waitcnt lgkmcnt(6)
	v_fmac_f32_e32 v20, v68, v47
	v_fmac_f32_e32 v21, v69, v47
	v_fmac_f32_e32 v22, v70, v47
	v_fmac_f32_e32 v23, v71, v47
	v_fmac_f32_e32 v24, v68, v51
	v_fmac_f32_e32 v25, v69, v51
	v_fmac_f32_e32 v26, v70, v51
	v_fmac_f32_e32 v27, v71, v51
	v_fmac_f32_e32 v28, v68, v55
	v_fmac_f32_e32 v29, v69, v55
	v_fmac_f32_e32 v30, v70, v55
	v_fmac_f32_e32 v31, v71, v55
	ds_read_b128 v[68:71], v3 offset:176
	ds_read_b128 v[44:47], v19 offset:48
	ds_read_b128 v[48:51], v19 offset:17456
	ds_read_b128 v[52:55], v2 offset:48
	s_waitcnt lgkmcnt(7)
	s_waitcnt lgkmcnt(6)
	v_fmac_f32_e32 v20, v56, v32
	v_fmac_f32_e32 v21, v57, v32
	v_fmac_f32_e32 v22, v58, v32
	v_fmac_f32_e32 v23, v59, v32
	v_fmac_f32_e32 v24, v56, v36
	v_fmac_f32_e32 v25, v57, v36
	v_fmac_f32_e32 v26, v58, v36
	v_fmac_f32_e32 v27, v59, v36
	v_fmac_f32_e32 v28, v56, v40
	v_fmac_f32_e32 v29, v57, v40
	v_fmac_f32_e32 v30, v58, v40
	v_fmac_f32_e32 v31, v59, v40
	ds_read_b128 v[56:59], v3 offset:192
	s_waitcnt lgkmcnt(6)
	v_fmac_f32_e32 v20, v60, v33
	v_fmac_f32_e32 v21, v61, v33
	v_fmac_f32_e32 v22, v62, v33
	v_fmac_f32_e32 v23, v63, v33
	v_fmac_f32_e32 v24, v60, v37
	v_fmac_f32_e32 v25, v61, v37
	v_fmac_f32_e32 v26, v62, v37
	v_fmac_f32_e32 v27, v63, v37
	v_fmac_f32_e32 v28, v60, v41
	v_fmac_f32_e32 v29, v61, v41
	v_fmac_f32_e32 v30, v62, v41
	v_fmac_f32_e32 v31, v63, v41
	ds_read_b128 v[60:63], v3 offset:208
	s_waitcnt lgkmcnt(6)
	v_fmac_f32_e32 v20, v64, v34
	v_fmac_f32_e32 v21, v65, v34
	v_fmac_f32_e32 v22, v66, v34
	v_fmac_f32_e32 v23, v67, v34
	v_fmac_f32_e32 v24, v64, v38
	v_fmac_f32_e32 v25, v65, v38
	v_fmac_f32_e32 v26, v66, v38
	v_fmac_f32_e32 v27, v67, v38
	v_fmac_f32_e32 v28, v64, v42
	v_fmac_f32_e32 v29, v65, v42
	v_fmac_f32_e32 v30, v66, v42
	v_fmac_f32_e32 v31, v67, v42
	ds_read_b128 v[64:67], v3 offset:224
	s_waitcnt lgkmcnt(6)
	v_fmac_f32_e32 v20, v68, v35
	v_fmac_f32_e32 v21, v69, v35
	v_fmac_f32_e32 v22, v70, v35
	v_fmac_f32_e32 v23, v71, v35
	v_fmac_f32_e32 v24, v68, v39
	v_fmac_f32_e32 v25, v69, v39
	v_fmac_f32_e32 v26, v70, v39
	v_fmac_f32_e32 v27, v71, v39
	v_fmac_f32_e32 v28, v68, v43
	v_fmac_f32_e32 v29, v69, v43
	v_fmac_f32_e32 v30, v70, v43
	v_fmac_f32_e32 v31, v71, v43
	ds_read_b128 v[68:71], v3 offset:240
	ds_read_b128 v[32:35], v19 offset:64
	ds_read_b128 v[36:39], v19 offset:17472
	ds_read_b128 v[40:43], v2 offset:64
	s_waitcnt lgkmcnt(7)
	s_waitcnt lgkmcnt(6)
	v_fmac_f32_e32 v20, v56, v44
	v_fmac_f32_e32 v21, v57, v44
	v_fmac_f32_e32 v22, v58, v44
	v_fmac_f32_e32 v23, v59, v44
	v_fmac_f32_e32 v24, v56, v48
	v_fmac_f32_e32 v25, v57, v48
	v_fmac_f32_e32 v26, v58, v48
	v_fmac_f32_e32 v27, v59, v48
	v_fmac_f32_e32 v28, v56, v52
	v_fmac_f32_e32 v29, v57, v52
	v_fmac_f32_e32 v30, v58, v52
	v_fmac_f32_e32 v31, v59, v52
	ds_read_b128 v[56:59], v3 offset:256
	s_waitcnt lgkmcnt(6)
	v_fmac_f32_e32 v20, v60, v45
	v_fmac_f32_e32 v21, v61, v45
	v_fmac_f32_e32 v22, v62, v45
	v_fmac_f32_e32 v23, v63, v45
	v_fmac_f32_e32 v24, v60, v49
	v_fmac_f32_e32 v25, v61, v49
	v_fmac_f32_e32 v26, v62, v49
	v_fmac_f32_e32 v27, v63, v49
	v_fmac_f32_e32 v28, v60, v53
	v_fmac_f32_e32 v29, v61, v53
	v_fmac_f32_e32 v30, v62, v53
	v_fmac_f32_e32 v31, v63, v53
	ds_read_b128 v[60:63], v3 offset:272
	s_waitcnt lgkmcnt(6)
	v_fmac_f32_e32 v20, v64, v46
	v_fmac_f32_e32 v21, v65, v46
	v_fmac_f32_e32 v22, v66, v46
	v_fmac_f32_e32 v23, v67, v46
	v_fmac_f32_e32 v24, v64, v50
	v_fmac_f32_e32 v25, v65, v50
	v_fmac_f32_e32 v26, v66, v50
	v_fmac_f32_e32 v27, v67, v50
	v_fmac_f32_e32 v28, v64, v54
	v_fmac_f32_e32 v29, v65, v54
	v_fmac_f32_e32 v30, v66, v54
	v_fmac_f32_e32 v31, v67, v54
	ds_read_b128 v[64:67], v3 offset:288
	s_waitcnt lgkmcnt(6)
	v_fmac_f32_e32 v20, v68, v47
	v_fmac_f32_e32 v21, v69, v47
	v_fmac_f32_e32 v22, v70, v47
	v_fmac_f32_e32 v23, v71, v47
	v_fmac_f32_e32 v24, v68, v51
	v_fmac_f32_e32 v25, v69, v51
	v_fmac_f32_e32 v26, v70, v51
	v_fmac_f32_e32 v27, v71, v51
	v_fmac_f32_e32 v28, v68, v55
	v_fmac_f32_e32 v29, v69, v55
	v_fmac_f32_e32 v30, v70, v55
	v_fmac_f32_e32 v31, v71, v55
	ds_read_b128 v[68:71], v3 offset:304
	ds_read_b128 v[44:47], v19 offset:80
	ds_read_b128 v[48:51], v19 offset:17488
	ds_read_b128 v[52:55], v2 offset:80
	s_waitcnt lgkmcnt(7)
	s_waitcnt lgkmcnt(6)
	v_fmac_f32_e32 v20, v56, v32
	v_fmac_f32_e32 v21, v57, v32
	v_fmac_f32_e32 v22, v58, v32
	v_fmac_f32_e32 v23, v59, v32
	v_fmac_f32_e32 v24, v56, v36
	v_fmac_f32_e32 v25, v57, v36
	v_fmac_f32_e32 v26, v58, v36
	v_fmac_f32_e32 v27, v59, v36
	v_fmac_f32_e32 v28, v56, v40
	v_fmac_f32_e32 v29, v57, v40
	v_fmac_f32_e32 v30, v58, v40
	v_fmac_f32_e32 v31, v59, v40
	ds_read_b128 v[56:59], v3 offset:320
	s_waitcnt lgkmcnt(6)
	v_fmac_f32_e32 v20, v60, v33
	v_fmac_f32_e32 v21, v61, v33
	v_fmac_f32_e32 v22, v62, v33
	v_fmac_f32_e32 v23, v63, v33
	v_fmac_f32_e32 v24, v60, v37
	v_fmac_f32_e32 v25, v61, v37
	v_fmac_f32_e32 v26, v62, v37
	v_fmac_f32_e32 v27, v63, v37
	v_fmac_f32_e32 v28, v60, v41
	v_fmac_f32_e32 v29, v61, v41
	v_fmac_f32_e32 v30, v62, v41
	v_fmac_f32_e32 v31, v63, v41
	ds_read_b128 v[60:63], v3 offset:336
	s_waitcnt lgkmcnt(6)
	v_fmac_f32_e32 v20, v64, v34
	v_fmac_f32_e32 v21, v65, v34
	v_fmac_f32_e32 v22, v66, v34
	v_fmac_f32_e32 v23, v67, v34
	v_fmac_f32_e32 v24, v64, v38
	v_fmac_f32_e32 v25, v65, v38
	v_fmac_f32_e32 v26, v66, v38
	v_fmac_f32_e32 v27, v67, v38
	v_fmac_f32_e32 v28, v64, v42
	v_fmac_f32_e32 v29, v65, v42
	v_fmac_f32_e32 v30, v66, v42
	v_fmac_f32_e32 v31, v67, v42
	ds_read_b128 v[64:67], v3 offset:352
	s_waitcnt lgkmcnt(6)
	v_fmac_f32_e32 v20, v68, v35
	v_fmac_f32_e32 v21, v69, v35
	v_fmac_f32_e32 v22, v70, v35
	v_fmac_f32_e32 v23, v71, v35
	v_fmac_f32_e32 v24, v68, v39
	v_fmac_f32_e32 v25, v69, v39
	v_fmac_f32_e32 v26, v70, v39
	v_fmac_f32_e32 v27, v71, v39
	v_fmac_f32_e32 v28, v68, v43
	v_fmac_f32_e32 v29, v69, v43
	v_fmac_f32_e32 v30, v70, v43
	v_fmac_f32_e32 v31, v71, v43
	ds_read_b128 v[68:71], v3 offset:368
	ds_read_b128 v[32:35], v19 offset:96
	ds_read_b128 v[36:39], v19 offset:17504
	ds_read_b128 v[40:43], v2 offset:96
	s_waitcnt lgkmcnt(7)
	s_waitcnt lgkmcnt(6)
	v_fmac_f32_e32 v20, v56, v44
	v_fmac_f32_e32 v21, v57, v44
	v_fmac_f32_e32 v22, v58, v44
	v_fmac_f32_e32 v23, v59, v44
	v_fmac_f32_e32 v24, v56, v48
	v_fmac_f32_e32 v25, v57, v48
	v_fmac_f32_e32 v26, v58, v48
	v_fmac_f32_e32 v27, v59, v48
	v_fmac_f32_e32 v28, v56, v52
	v_fmac_f32_e32 v29, v57, v52
	v_fmac_f32_e32 v30, v58, v52
	v_fmac_f32_e32 v31, v59, v52
	ds_read_b128 v[56:59], v3 offset:384
	s_waitcnt lgkmcnt(6)
	v_fmac_f32_e32 v20, v60, v45
	v_fmac_f32_e32 v21, v61, v45
	v_fmac_f32_e32 v22, v62, v45
	v_fmac_f32_e32 v23, v63, v45
	v_fmac_f32_e32 v24, v60, v49
	v_fmac_f32_e32 v25, v61, v49
	v_fmac_f32_e32 v26, v62, v49
	v_fmac_f32_e32 v27, v63, v49
	v_fmac_f32_e32 v28, v60, v53
	v_fmac_f32_e32 v29, v61, v53
	v_fmac_f32_e32 v30, v62, v53
	v_fmac_f32_e32 v31, v63, v53
	ds_read_b128 v[60:63], v3 offset:400
	s_waitcnt lgkmcnt(6)
	v_fmac_f32_e32 v20, v64, v46
	v_fmac_f32_e32 v21, v65, v46
	v_fmac_f32_e32 v22, v66, v46
	v_fmac_f32_e32 v23, v67, v46
	v_fmac_f32_e32 v24, v64, v50
	v_fmac_f32_e32 v25, v65, v50
	v_fmac_f32_e32 v26, v66, v50
	v_fmac_f32_e32 v27, v67, v50
	v_fmac_f32_e32 v28, v64, v54
	v_fmac_f32_e32 v29, v65, v54
	v_fmac_f32_e32 v30, v66, v54
	v_fmac_f32_e32 v31, v67, v54
	ds_read_b128 v[64:67], v3 offset:416
	s_waitcnt lgkmcnt(6)
	v_fmac_f32_e32 v20, v68, v47
	v_fmac_f32_e32 v21, v69, v47
	v_fmac_f32_e32 v22, v70, v47
	v_fmac_f32_e32 v23, v71, v47
	v_fmac_f32_e32 v24, v68, v51
	v_fmac_f32_e32 v25, v69, v51
	v_fmac_f32_e32 v26, v70, v51
	v_fmac_f32_e32 v27, v71, v51
	v_fmac_f32_e32 v28, v68, v55
	v_fmac_f32_e32 v29, v69, v55
	v_fmac_f32_e32 v30, v70, v55
	v_fmac_f32_e32 v31, v71, v55
	ds_read_b128 v[68:71], v3 offset:432
	ds_read_b128 v[44:47], v19 offset:112
	ds_read_b128 v[48:51], v19 offset:17520
	ds_read_b128 v[52:55], v2 offset:112
	s_waitcnt lgkmcnt(7)
	s_waitcnt lgkmcnt(6)
	v_fmac_f32_e32 v20, v56, v32
	v_fmac_f32_e32 v21, v57, v32
	v_fmac_f32_e32 v22, v58, v32
	v_fmac_f32_e32 v23, v59, v32
	v_fmac_f32_e32 v24, v56, v36
	v_fmac_f32_e32 v25, v57, v36
	v_fmac_f32_e32 v26, v58, v36
	v_fmac_f32_e32 v27, v59, v36
	v_fmac_f32_e32 v28, v56, v40
	v_fmac_f32_e32 v29, v57, v40
	v_fmac_f32_e32 v30, v58, v40
	v_fmac_f32_e32 v31, v59, v40
	ds_read_b128 v[56:59], v3 offset:448
	s_waitcnt lgkmcnt(6)
	v_fmac_f32_e32 v20, v60, v33
	v_fmac_f32_e32 v21, v61, v33
	v_fmac_f32_e32 v22, v62, v33
	v_fmac_f32_e32 v23, v63, v33
	v_fmac_f32_e32 v24, v60, v37
	v_fmac_f32_e32 v25, v61, v37
	v_fmac_f32_e32 v26, v62, v37
	v_fmac_f32_e32 v27, v63, v37
	v_fmac_f32_e32 v28, v60, v41
	v_fmac_f32_e32 v29, v61, v41
	v_fmac_f32_e32 v30, v62, v41
	v_fmac_f32_e32 v31, v63, v41
	ds_read_b128 v[60:63], v3 offset:464
	s_waitcnt lgkmcnt(6)
	v_fmac_f32_e32 v20, v64, v34
	v_fmac_f32_e32 v21, v65, v34
	v_fmac_f32_e32 v22, v66, v34
	v_fmac_f32_e32 v23, v67, v34
	v_fmac_f32_e32 v24, v64, v38
	v_fmac_f32_e32 v25, v65, v38
	v_fmac_f32_e32 v26, v66, v38
	v_fmac_f32_e32 v27, v67, v38
	v_fmac_f32_e32 v28, v64, v42
	v_fmac_f32_e32 v29, v65, v42
	v_fmac_f32_e32 v30, v66, v42
	v_fmac_f32_e32 v31, v67, v42
	ds_read_b128 v[64:67], v3 offset:480
	s_waitcnt lgkmcnt(6)
	v_fmac_f32_e32 v20, v68, v35
	v_fmac_f32_e32 v21, v69, v35
	v_fmac_f32_e32 v22, v70, v35
	v_fmac_f32_e32 v23, v71, v35
	v_fmac_f32_e32 v24, v68, v39
	v_fmac_f32_e32 v25, v69, v39
	v_fmac_f32_e32 v26, v70, v39
	v_fmac_f32_e32 v27, v71, v39
	v_fmac_f32_e32 v28, v68, v43
	v_fmac_f32_e32 v29, v69, v43
	v_fmac_f32_e32 v30, v70, v43
	v_fmac_f32_e32 v31, v71, v43
	ds_read_b128 v[68:71], v3 offset:496
	ds_read_b128 v[32:35], v19 offset:128
	ds_read_b128 v[36:39], v19 offset:17536
	ds_read_b128 v[40:43], v2 offset:128
	s_waitcnt lgkmcnt(7)
	s_waitcnt lgkmcnt(6)
	v_fmac_f32_e32 v20, v56, v44
	v_fmac_f32_e32 v21, v57, v44
	v_fmac_f32_e32 v22, v58, v44
	v_fmac_f32_e32 v23, v59, v44
	v_fmac_f32_e32 v24, v56, v48
	v_fmac_f32_e32 v25, v57, v48
	v_fmac_f32_e32 v26, v58, v48
	v_fmac_f32_e32 v27, v59, v48
	v_fmac_f32_e32 v28, v56, v52
	v_fmac_f32_e32 v29, v57, v52
	v_fmac_f32_e32 v30, v58, v52
	v_fmac_f32_e32 v31, v59, v52
	ds_read_b128 v[56:59], v3 offset:512
	s_waitcnt lgkmcnt(6)
	v_fmac_f32_e32 v20, v60, v45
	v_fmac_f32_e32 v21, v61, v45
	v_fmac_f32_e32 v22, v62, v45
	v_fmac_f32_e32 v23, v63, v45
	v_fmac_f32_e32 v24, v60, v49
	v_fmac_f32_e32 v25, v61, v49
	v_fmac_f32_e32 v26, v62, v49
	v_fmac_f32_e32 v27, v63, v49
	v_fmac_f32_e32 v28, v60, v53
	v_fmac_f32_e32 v29, v61, v53
	v_fmac_f32_e32 v30, v62, v53
	v_fmac_f32_e32 v31, v63, v53
	ds_read_b128 v[60:63], v3 offset:528
	s_waitcnt lgkmcnt(6)
	v_fmac_f32_e32 v20, v64, v46
	v_fmac_f32_e32 v21, v65, v46
	v_fmac_f32_e32 v22, v66, v46
	v_fmac_f32_e32 v23, v67, v46
	v_fmac_f32_e32 v24, v64, v50
	v_fmac_f32_e32 v25, v65, v50
	v_fmac_f32_e32 v26, v66, v50
	v_fmac_f32_e32 v27, v67, v50
	v_fmac_f32_e32 v28, v64, v54
	v_fmac_f32_e32 v29, v65, v54
	v_fmac_f32_e32 v30, v66, v54
	v_fmac_f32_e32 v31, v67, v54
	ds_read_b128 v[64:67], v3 offset:544
	s_waitcnt lgkmcnt(6)
	v_fmac_f32_e32 v20, v68, v47
	v_fmac_f32_e32 v21, v69, v47
	v_fmac_f32_e32 v22, v70, v47
	v_fmac_f32_e32 v23, v71, v47
	v_fmac_f32_e32 v24, v68, v51
	v_fmac_f32_e32 v25, v69, v51
	v_fmac_f32_e32 v26, v70, v51
	v_fmac_f32_e32 v27, v71, v51
	v_fmac_f32_e32 v28, v68, v55
	v_fmac_f32_e32 v29, v69, v55
	v_fmac_f32_e32 v30, v70, v55
	v_fmac_f32_e32 v31, v71, v55
	ds_read_b128 v[68:71], v3 offset:560
	ds_read_b128 v[44:47], v19 offset:144
	ds_read_b128 v[48:51], v19 offset:17552
	ds_read_b128 v[52:55], v2 offset:144
	s_waitcnt lgkmcnt(7)
	s_waitcnt lgkmcnt(6)
	v_fmac_f32_e32 v20, v56, v32
	v_fmac_f32_e32 v21, v57, v32
	v_fmac_f32_e32 v22, v58, v32
	v_fmac_f32_e32 v23, v59, v32
	v_fmac_f32_e32 v24, v56, v36
	v_fmac_f32_e32 v25, v57, v36
	v_fmac_f32_e32 v26, v58, v36
	v_fmac_f32_e32 v27, v59, v36
	v_fmac_f32_e32 v28, v56, v40
	v_fmac_f32_e32 v29, v57, v40
	v_fmac_f32_e32 v30, v58, v40
	v_fmac_f32_e32 v31, v59, v40
	ds_read_b128 v[56:59], v3 offset:576
	s_waitcnt lgkmcnt(6)
	v_fmac_f32_e32 v20, v60, v33
	v_fmac_f32_e32 v21, v61, v33
	v_fmac_f32_e32 v22, v62, v33
	v_fmac_f32_e32 v23, v63, v33
	v_fmac_f32_e32 v24, v60, v37
	v_fmac_f32_e32 v25, v61, v37
	v_fmac_f32_e32 v26, v62, v37
	v_fmac_f32_e32 v27, v63, v37
	v_fmac_f32_e32 v28, v60, v41
	v_fmac_f32_e32 v29, v61, v41
	v_fmac_f32_e32 v30, v62, v41
	v_fmac_f32_e32 v31, v63, v41
	ds_read_b128 v[60:63], v3 offset:592
	s_waitcnt lgkmcnt(6)
	v_fmac_f32_e32 v20, v64, v34
	v_fmac_f32_e32 v21, v65, v34
	v_fmac_f32_e32 v22, v66, v34
	v_fmac_f32_e32 v23, v67, v34
	v_fmac_f32_e32 v24, v64, v38
	v_fmac_f32_e32 v25, v65, v38
	v_fmac_f32_e32 v26, v66, v38
	v_fmac_f32_e32 v27, v67, v38
	v_fmac_f32_e32 v28, v64, v42
	v_fmac_f32_e32 v29, v65, v42
	v_fmac_f32_e32 v30, v66, v42
	v_fmac_f32_e32 v31, v67, v42
	ds_read_b128 v[64:67], v3 offset:608
	s_waitcnt lgkmcnt(6)
	v_fmac_f32_e32 v20, v68, v35
	v_fmac_f32_e32 v21, v69, v35
	v_fmac_f32_e32 v22, v70, v35
	v_fmac_f32_e32 v23, v71, v35
	v_fmac_f32_e32 v24, v68, v39
	v_fmac_f32_e32 v25, v69, v39
	v_fmac_f32_e32 v26, v70, v39
	v_fmac_f32_e32 v27, v71, v39
	v_fmac_f32_e32 v28, v68, v43
	v_fmac_f32_e32 v29, v69, v43
	v_fmac_f32_e32 v30, v70, v43
	v_fmac_f32_e32 v31, v71, v43
	ds_read_b128 v[68:71], v3 offset:624
	ds_read_b128 v[32:35], v19 offset:160
	ds_read_b128 v[36:39], v19 offset:17568
	ds_read_b128 v[40:43], v2 offset:160
	s_waitcnt lgkmcnt(7)
	s_waitcnt lgkmcnt(6)
	v_fmac_f32_e32 v20, v56, v44
	v_fmac_f32_e32 v21, v57, v44
	v_fmac_f32_e32 v22, v58, v44
	v_fmac_f32_e32 v23, v59, v44
	v_fmac_f32_e32 v24, v56, v48
	v_fmac_f32_e32 v25, v57, v48
	v_fmac_f32_e32 v26, v58, v48
	v_fmac_f32_e32 v27, v59, v48
	v_fmac_f32_e32 v28, v56, v52
	v_fmac_f32_e32 v29, v57, v52
	v_fmac_f32_e32 v30, v58, v52
	v_fmac_f32_e32 v31, v59, v52
	ds_read_b128 v[56:59], v3 offset:640
	s_waitcnt lgkmcnt(6)
	v_fmac_f32_e32 v20, v60, v45
	v_fmac_f32_e32 v21, v61, v45
	v_fmac_f32_e32 v22, v62, v45
	v_fmac_f32_e32 v23, v63, v45
	v_fmac_f32_e32 v24, v60, v49
	v_fmac_f32_e32 v25, v61, v49
	v_fmac_f32_e32 v26, v62, v49
	v_fmac_f32_e32 v27, v63, v49
	v_fmac_f32_e32 v28, v60, v53
	v_fmac_f32_e32 v29, v61, v53
	v_fmac_f32_e32 v30, v62, v53
	v_fmac_f32_e32 v31, v63, v53
	ds_read_b128 v[60:63], v3 offset:656
	s_waitcnt lgkmcnt(6)
	v_fmac_f32_e32 v20, v64, v46
	v_fmac_f32_e32 v21, v65, v46
	v_fmac_f32_e32 v22, v66, v46
	v_fmac_f32_e32 v23, v67, v46
	v_fmac_f32_e32 v24, v64, v50
	v_fmac_f32_e32 v25, v65, v50
	v_fmac_f32_e32 v26, v66, v50
	v_fmac_f32_e32 v27, v67, v50
	v_fmac_f32_e32 v28, v64, v54
	v_fmac_f32_e32 v29, v65, v54
	v_fmac_f32_e32 v30, v66, v54
	v_fmac_f32_e32 v31, v67, v54
	ds_read_b128 v[64:67], v3 offset:672
	s_waitcnt lgkmcnt(6)
	v_fmac_f32_e32 v20, v68, v47
	v_fmac_f32_e32 v21, v69, v47
	v_fmac_f32_e32 v22, v70, v47
	v_fmac_f32_e32 v23, v71, v47
	v_fmac_f32_e32 v24, v68, v51
	v_fmac_f32_e32 v25, v69, v51
	v_fmac_f32_e32 v26, v70, v51
	v_fmac_f32_e32 v27, v71, v51
	v_fmac_f32_e32 v28, v68, v55
	v_fmac_f32_e32 v29, v69, v55
	v_fmac_f32_e32 v30, v70, v55
	v_fmac_f32_e32 v31, v71, v55
	ds_read_b128 v[68:71], v3 offset:688
	ds_read_b128 v[44:47], v19 offset:176
	ds_read_b128 v[48:51], v19 offset:17584
	ds_read_b128 v[52:55], v2 offset:176
	s_waitcnt lgkmcnt(7)
	s_waitcnt lgkmcnt(6)
	v_fmac_f32_e32 v20, v56, v32
	v_fmac_f32_e32 v21, v57, v32
	v_fmac_f32_e32 v22, v58, v32
	v_fmac_f32_e32 v23, v59, v32
	v_fmac_f32_e32 v24, v56, v36
	v_fmac_f32_e32 v25, v57, v36
	v_fmac_f32_e32 v26, v58, v36
	v_fmac_f32_e32 v27, v59, v36
	v_fmac_f32_e32 v28, v56, v40
	v_fmac_f32_e32 v29, v57, v40
	v_fmac_f32_e32 v30, v58, v40
	v_fmac_f32_e32 v31, v59, v40
	ds_read_b128 v[56:59], v3 offset:704
	s_waitcnt lgkmcnt(6)
	v_fmac_f32_e32 v20, v60, v33
	v_fmac_f32_e32 v21, v61, v33
	v_fmac_f32_e32 v22, v62, v33
	v_fmac_f32_e32 v23, v63, v33
	v_fmac_f32_e32 v24, v60, v37
	v_fmac_f32_e32 v25, v61, v37
	v_fmac_f32_e32 v26, v62, v37
	v_fmac_f32_e32 v27, v63, v37
	v_fmac_f32_e32 v28, v60, v41
	v_fmac_f32_e32 v29, v61, v41
	v_fmac_f32_e32 v30, v62, v41
	v_fmac_f32_e32 v31, v63, v41
	ds_read_b128 v[60:63], v3 offset:720
	s_waitcnt lgkmcnt(6)
	v_fmac_f32_e32 v20, v64, v34
	v_fmac_f32_e32 v21, v65, v34
	v_fmac_f32_e32 v22, v66, v34
	v_fmac_f32_e32 v23, v67, v34
	v_fmac_f32_e32 v24, v64, v38
	v_fmac_f32_e32 v25, v65, v38
	v_fmac_f32_e32 v26, v66, v38
	v_fmac_f32_e32 v27, v67, v38
	v_fmac_f32_e32 v28, v64, v42
	v_fmac_f32_e32 v29, v65, v42
	v_fmac_f32_e32 v30, v66, v42
	v_fmac_f32_e32 v31, v67, v42
	ds_read_b128 v[64:67], v3 offset:736
	s_waitcnt lgkmcnt(6)
	v_fmac_f32_e32 v20, v68, v35
	v_fmac_f32_e32 v21, v69, v35
	v_fmac_f32_e32 v22, v70, v35
	v_fmac_f32_e32 v23, v71, v35
	v_fmac_f32_e32 v24, v68, v39
	v_fmac_f32_e32 v25, v69, v39
	v_fmac_f32_e32 v26, v70, v39
	v_fmac_f32_e32 v27, v71, v39
	v_fmac_f32_e32 v28, v68, v43
	v_fmac_f32_e32 v29, v69, v43
	v_fmac_f32_e32 v30, v70, v43
	v_fmac_f32_e32 v31, v71, v43
	ds_read_b128 v[68:71], v3 offset:752
	ds_read_b128 v[32:35], v19 offset:192
	ds_read_b128 v[36:39], v19 offset:17600
	ds_read_b128 v[40:43], v2 offset:192
	s_waitcnt lgkmcnt(7)
	s_waitcnt lgkmcnt(6)
	v_fmac_f32_e32 v20, v56, v44
	v_fmac_f32_e32 v21, v57, v44
	v_fmac_f32_e32 v22, v58, v44
	v_fmac_f32_e32 v23, v59, v44
	v_fmac_f32_e32 v24, v56, v48
	v_fmac_f32_e32 v25, v57, v48
	v_fmac_f32_e32 v26, v58, v48
	v_fmac_f32_e32 v27, v59, v48
	v_fmac_f32_e32 v28, v56, v52
	v_fmac_f32_e32 v29, v57, v52
	v_fmac_f32_e32 v30, v58, v52
	v_fmac_f32_e32 v31, v59, v52
	ds_read_b128 v[56:59], v3 offset:768
	s_waitcnt lgkmcnt(6)
	v_fmac_f32_e32 v20, v60, v45
	v_fmac_f32_e32 v21, v61, v45
	v_fmac_f32_e32 v22, v62, v45
	v_fmac_f32_e32 v23, v63, v45
	v_fmac_f32_e32 v24, v60, v49
	v_fmac_f32_e32 v25, v61, v49
	v_fmac_f32_e32 v26, v62, v49
	v_fmac_f32_e32 v27, v63, v49
	v_fmac_f32_e32 v28, v60, v53
	v_fmac_f32_e32 v29, v61, v53
	v_fmac_f32_e32 v30, v62, v53
	v_fmac_f32_e32 v31, v63, v53
	ds_read_b128 v[60:63], v3 offset:784
	s_waitcnt lgkmcnt(6)
	v_fmac_f32_e32 v20, v64, v46
	v_fmac_f32_e32 v21, v65, v46
	v_fmac_f32_e32 v22, v66, v46
	v_fmac_f32_e32 v23, v67, v46
	v_fmac_f32_e32 v24, v64, v50
	v_fmac_f32_e32 v25, v65, v50
	v_fmac_f32_e32 v26, v66, v50
	v_fmac_f32_e32 v27, v67, v50
	v_fmac_f32_e32 v28, v64, v54
	v_fmac_f32_e32 v29, v65, v54
	v_fmac_f32_e32 v30, v66, v54
	v_fmac_f32_e32 v31, v67, v54
	ds_read_b128 v[64:67], v3 offset:800
	s_waitcnt lgkmcnt(6)
	v_fmac_f32_e32 v20, v68, v47
	v_fmac_f32_e32 v21, v69, v47
	v_fmac_f32_e32 v22, v70, v47
	v_fmac_f32_e32 v23, v71, v47
	v_fmac_f32_e32 v24, v68, v51
	v_fmac_f32_e32 v25, v69, v51
	v_fmac_f32_e32 v26, v70, v51
	v_fmac_f32_e32 v27, v71, v51
	v_fmac_f32_e32 v28, v68, v55
	v_fmac_f32_e32 v29, v69, v55
	v_fmac_f32_e32 v30, v70, v55
	v_fmac_f32_e32 v31, v71, v55
	ds_read_b128 v[68:71], v3 offset:816
	ds_read_b128 v[44:47], v19 offset:208
	ds_read_b128 v[48:51], v19 offset:17616
	ds_read_b128 v[52:55], v2 offset:208
	s_waitcnt lgkmcnt(7)
	s_waitcnt lgkmcnt(6)
	v_fmac_f32_e32 v20, v56, v32
	v_fmac_f32_e32 v21, v57, v32
	v_fmac_f32_e32 v22, v58, v32
	v_fmac_f32_e32 v23, v59, v32
	v_fmac_f32_e32 v24, v56, v36
	v_fmac_f32_e32 v25, v57, v36
	v_fmac_f32_e32 v26, v58, v36
	v_fmac_f32_e32 v27, v59, v36
	v_fmac_f32_e32 v28, v56, v40
	v_fmac_f32_e32 v29, v57, v40
	v_fmac_f32_e32 v30, v58, v40
	v_fmac_f32_e32 v31, v59, v40
	ds_read_b128 v[56:59], v3 offset:832
	s_waitcnt lgkmcnt(6)
	v_fmac_f32_e32 v20, v60, v33
	v_fmac_f32_e32 v21, v61, v33
	v_fmac_f32_e32 v22, v62, v33
	v_fmac_f32_e32 v23, v63, v33
	v_fmac_f32_e32 v24, v60, v37
	v_fmac_f32_e32 v25, v61, v37
	v_fmac_f32_e32 v26, v62, v37
	v_fmac_f32_e32 v27, v63, v37
	v_fmac_f32_e32 v28, v60, v41
	v_fmac_f32_e32 v29, v61, v41
	v_fmac_f32_e32 v30, v62, v41
	v_fmac_f32_e32 v31, v63, v41
	ds_read_b128 v[60:63], v3 offset:848
	s_waitcnt lgkmcnt(6)
	v_fmac_f32_e32 v20, v64, v34
	v_fmac_f32_e32 v21, v65, v34
	v_fmac_f32_e32 v22, v66, v34
	v_fmac_f32_e32 v23, v67, v34
	v_fmac_f32_e32 v24, v64, v38
	v_fmac_f32_e32 v25, v65, v38
	v_fmac_f32_e32 v26, v66, v38
	v_fmac_f32_e32 v27, v67, v38
	v_fmac_f32_e32 v28, v64, v42
	v_fmac_f32_e32 v29, v65, v42
	v_fmac_f32_e32 v30, v66, v42
	v_fmac_f32_e32 v31, v67, v42
	ds_read_b128 v[64:67], v3 offset:864
	s_waitcnt lgkmcnt(6)
	v_fmac_f32_e32 v20, v68, v35
	v_fmac_f32_e32 v21, v69, v35
	v_fmac_f32_e32 v22, v70, v35
	v_fmac_f32_e32 v23, v71, v35
	v_fmac_f32_e32 v24, v68, v39
	v_fmac_f32_e32 v25, v69, v39
	v_fmac_f32_e32 v26, v70, v39
	v_fmac_f32_e32 v27, v71, v39
	v_fmac_f32_e32 v28, v68, v43
	v_fmac_f32_e32 v29, v69, v43
	v_fmac_f32_e32 v30, v70, v43
	v_fmac_f32_e32 v31, v71, v43
	ds_read_b128 v[68:71], v3 offset:880
	ds_read_b128 v[32:35], v19 offset:224
	ds_read_b128 v[36:39], v19 offset:17632
	ds_read_b128 v[40:43], v2 offset:224
	s_waitcnt lgkmcnt(7)
	s_waitcnt lgkmcnt(6)
	v_fmac_f32_e32 v20, v56, v44
	v_fmac_f32_e32 v21, v57, v44
	v_fmac_f32_e32 v22, v58, v44
	v_fmac_f32_e32 v23, v59, v44
	v_fmac_f32_e32 v24, v56, v48
	v_fmac_f32_e32 v25, v57, v48
	v_fmac_f32_e32 v26, v58, v48
	v_fmac_f32_e32 v27, v59, v48
	v_fmac_f32_e32 v28, v56, v52
	v_fmac_f32_e32 v29, v57, v52
	v_fmac_f32_e32 v30, v58, v52
	v_fmac_f32_e32 v31, v59, v52
	ds_read_b128 v[56:59], v3 offset:896
	s_waitcnt lgkmcnt(6)
	v_fmac_f32_e32 v20, v60, v45
	v_fmac_f32_e32 v21, v61, v45
	v_fmac_f32_e32 v22, v62, v45
	v_fmac_f32_e32 v23, v63, v45
	v_fmac_f32_e32 v24, v60, v49
	v_fmac_f32_e32 v25, v61, v49
	v_fmac_f32_e32 v26, v62, v49
	v_fmac_f32_e32 v27, v63, v49
	v_fmac_f32_e32 v28, v60, v53
	v_fmac_f32_e32 v29, v61, v53
	v_fmac_f32_e32 v30, v62, v53
	v_fmac_f32_e32 v31, v63, v53
	ds_read_b128 v[60:63], v3 offset:912
	s_waitcnt lgkmcnt(6)
	v_fmac_f32_e32 v20, v64, v46
	v_fmac_f32_e32 v21, v65, v46
	v_fmac_f32_e32 v22, v66, v46
	v_fmac_f32_e32 v23, v67, v46
	v_fmac_f32_e32 v24, v64, v50
	v_fmac_f32_e32 v25, v65, v50
	v_fmac_f32_e32 v26, v66, v50
	v_fmac_f32_e32 v27, v67, v50
	v_fmac_f32_e32 v28, v64, v54
	v_fmac_f32_e32 v29, v65, v54
	v_fmac_f32_e32 v30, v66, v54
	v_fmac_f32_e32 v31, v67, v54
	ds_read_b128 v[64:67], v3 offset:928
	s_waitcnt lgkmcnt(6)
	v_fmac_f32_e32 v20, v68, v47
	v_fmac_f32_e32 v21, v69, v47
	v_fmac_f32_e32 v22, v70, v47
	v_fmac_f32_e32 v23, v71, v47
	v_fmac_f32_e32 v24, v68, v51
	v_fmac_f32_e32 v25, v69, v51
	v_fmac_f32_e32 v26, v70, v51
	v_fmac_f32_e32 v27, v71, v51
	v_fmac_f32_e32 v28, v68, v55
	v_fmac_f32_e32 v29, v69, v55
	v_fmac_f32_e32 v30, v70, v55
	v_fmac_f32_e32 v31, v71, v55
	ds_read_b128 v[68:71], v3 offset:944
	ds_read_b128 v[44:47], v19 offset:240
	ds_read_b128 v[48:51], v19 offset:17648
	ds_read_b128 v[52:55], v2 offset:240
	s_waitcnt lgkmcnt(7)
	s_waitcnt lgkmcnt(6)
	v_fmac_f32_e32 v20, v56, v32
	v_fmac_f32_e32 v21, v57, v32
	v_fmac_f32_e32 v22, v58, v32
	v_fmac_f32_e32 v23, v59, v32
	v_fmac_f32_e32 v24, v56, v36
	v_fmac_f32_e32 v25, v57, v36
	v_fmac_f32_e32 v26, v58, v36
	v_fmac_f32_e32 v27, v59, v36
	v_fmac_f32_e32 v28, v56, v40
	v_fmac_f32_e32 v29, v57, v40
	v_fmac_f32_e32 v30, v58, v40
	v_fmac_f32_e32 v31, v59, v40
	ds_read_b128 v[56:59], v3 offset:960
	s_waitcnt lgkmcnt(6)
	v_fmac_f32_e32 v20, v60, v33
	v_fmac_f32_e32 v21, v61, v33
	v_fmac_f32_e32 v22, v62, v33
	v_fmac_f32_e32 v23, v63, v33
	v_fmac_f32_e32 v24, v60, v37
	v_fmac_f32_e32 v25, v61, v37
	v_fmac_f32_e32 v26, v62, v37
	v_fmac_f32_e32 v27, v63, v37
	v_fmac_f32_e32 v28, v60, v41
	v_fmac_f32_e32 v29, v61, v41
	v_fmac_f32_e32 v30, v62, v41
	v_fmac_f32_e32 v31, v63, v41
	ds_read_b128 v[60:63], v3 offset:976
	s_waitcnt lgkmcnt(6)
	v_fmac_f32_e32 v20, v64, v34
	v_fmac_f32_e32 v21, v65, v34
	v_fmac_f32_e32 v22, v66, v34
	v_fmac_f32_e32 v23, v67, v34
	v_fmac_f32_e32 v24, v64, v38
	v_fmac_f32_e32 v25, v65, v38
	v_fmac_f32_e32 v26, v66, v38
	v_fmac_f32_e32 v27, v67, v38
	v_fmac_f32_e32 v28, v64, v42
	v_fmac_f32_e32 v29, v65, v42
	v_fmac_f32_e32 v30, v66, v42
	v_fmac_f32_e32 v31, v67, v42
	ds_read_b128 v[64:67], v3 offset:992
	s_waitcnt lgkmcnt(6)
	v_fmac_f32_e32 v20, v68, v35
	v_fmac_f32_e32 v21, v69, v35
	v_fmac_f32_e32 v22, v70, v35
	v_fmac_f32_e32 v23, v71, v35
	v_fmac_f32_e32 v24, v68, v39
	v_fmac_f32_e32 v25, v69, v39
	v_fmac_f32_e32 v26, v70, v39
	v_fmac_f32_e32 v27, v71, v39
	v_fmac_f32_e32 v28, v68, v43
	v_fmac_f32_e32 v29, v69, v43
	v_fmac_f32_e32 v30, v70, v43
	v_fmac_f32_e32 v31, v71, v43
	ds_read_b128 v[68:71], v3 offset:1008
	s_waitcnt lgkmcnt(4)
	s_waitcnt lgkmcnt(3)
	v_fmac_f32_e32 v20, v56, v44
	v_fmac_f32_e32 v21, v57, v44
	v_fmac_f32_e32 v22, v58, v44
	v_fmac_f32_e32 v23, v59, v44
	v_fmac_f32_e32 v24, v56, v48
	v_fmac_f32_e32 v25, v57, v48
	v_fmac_f32_e32 v26, v58, v48
	v_fmac_f32_e32 v27, v59, v48
	v_fmac_f32_e32 v28, v56, v52
	v_fmac_f32_e32 v29, v57, v52
	v_fmac_f32_e32 v30, v58, v52
	v_fmac_f32_e32 v31, v59, v52
	s_waitcnt lgkmcnt(2)
	v_fmac_f32_e32 v20, v60, v45
	v_fmac_f32_e32 v21, v61, v45
	v_fmac_f32_e32 v22, v62, v45
	v_fmac_f32_e32 v23, v63, v45
	v_fmac_f32_e32 v24, v60, v49
	v_fmac_f32_e32 v25, v61, v49
	v_fmac_f32_e32 v26, v62, v49
	v_fmac_f32_e32 v27, v63, v49
	v_fmac_f32_e32 v28, v60, v53
	v_fmac_f32_e32 v29, v61, v53
	v_fmac_f32_e32 v30, v62, v53
	v_fmac_f32_e32 v31, v63, v53
	s_waitcnt lgkmcnt(1)
	v_fmac_f32_e32 v20, v64, v46
	v_fmac_f32_e32 v21, v65, v46
	v_fmac_f32_e32 v22, v66, v46
	v_fmac_f32_e32 v23, v67, v46
	v_fmac_f32_e32 v24, v64, v50
	v_fmac_f32_e32 v25, v65, v50
	v_fmac_f32_e32 v26, v66, v50
	v_fmac_f32_e32 v27, v67, v50
	v_fmac_f32_e32 v28, v64, v54
	v_fmac_f32_e32 v29, v65, v54
	v_fmac_f32_e32 v30, v66, v54
	v_fmac_f32_e32 v31, v67, v54
	s_waitcnt lgkmcnt(0)
	v_fmac_f32_e32 v20, v68, v47
	v_fmac_f32_e32 v21, v69, v47
	v_fmac_f32_e32 v22, v70, v47
	v_fmac_f32_e32 v23, v71, v47
	v_fmac_f32_e32 v24, v68, v51
	v_fmac_f32_e32 v25, v69, v51
	v_fmac_f32_e32 v26, v70, v51
	v_fmac_f32_e32 v27, v71, v51
	v_fmac_f32_e32 v28, v68, v55
	v_fmac_f32_e32 v29, v69, v55
	v_fmac_f32_e32 v30, v70, v55
	v_fmac_f32_e32 v31, v71, v55
	s_add_u32 s8, s10, 0x14180000
	s_addc_u32 s9, s11, 0
	s_lshl_b32 s2, s44, 9
	s_add_u32 s8, s8, s2
	s_addc_u32 s9, s9, 0
	v_sub_u32_e32 v44, 128, v7
	v_and_b32_e32 v44, 0x7f, v44
	v_lshlrev_b32_e32 v44, 2, v44
	global_load_dword v32, v44, s[8:9]
	v_sub_u32_e32 v44, 129, v7
	v_and_b32_e32 v44, 0x7f, v44
	v_lshlrev_b32_e32 v44, 2, v44
	global_load_dword v33, v44, s[8:9]
	v_sub_u32_e32 v44, 130, v7
	v_and_b32_e32 v44, 0x7f, v44
	v_lshlrev_b32_e32 v44, 2, v44
	global_load_dword v34, v44, s[8:9]
	v_sub_u32_e32 v44, 131, v7
	v_and_b32_e32 v44, 0x7f, v44
	v_lshlrev_b32_e32 v44, 2, v44
	global_load_dword v35, v44, s[8:9]
	v_sub_u32_e32 v44, 64, v7
	v_and_b32_e32 v44, 0x7f, v44
	v_lshlrev_b32_e32 v44, 2, v44
	global_load_dword v36, v44, s[8:9]
	v_sub_u32_e32 v44, 65, v7
	v_and_b32_e32 v44, 0x7f, v44
	v_lshlrev_b32_e32 v44, 2, v44
	global_load_dword v37, v44, s[8:9]
	v_sub_u32_e32 v44, 66, v7
	v_and_b32_e32 v44, 0x7f, v44
	v_lshlrev_b32_e32 v44, 2, v44
	global_load_dword v38, v44, s[8:9]
	v_sub_u32_e32 v44, 67, v7
	v_and_b32_e32 v44, 0x7f, v44
	v_lshlrev_b32_e32 v44, 2, v44
	global_load_dword v39, v44, s[8:9]
	v_sub_u32_e32 v44, 0, v7
	v_and_b32_e32 v44, 0x7f, v44
	v_lshlrev_b32_e32 v44, 2, v44
	global_load_dword v40, v44, s[8:9]
	v_sub_u32_e32 v44, 1, v7
	v_and_b32_e32 v44, 0x7f, v44
	v_lshlrev_b32_e32 v44, 2, v44
	global_load_dword v41, v44, s[8:9]
	v_sub_u32_e32 v44, 2, v7
	v_and_b32_e32 v44, 0x7f, v44
	v_lshlrev_b32_e32 v44, 2, v44
	global_load_dword v42, v44, s[8:9]
	v_sub_u32_e32 v44, 3, v7
	v_and_b32_e32 v44, 0x7f, v44
	v_lshlrev_b32_e32 v44, 2, v44
	global_load_dword v43, v44, s[8:9]
	s_waitcnt vmcnt(0)
	v_add_f32_e32 v20, v20, v32
	v_add_f32_e32 v21, v21, v33
	v_add_f32_e32 v22, v22, v34
	v_add_f32_e32 v23, v23, v35
	v_add_f32_e32 v24, v24, v36
	v_add_f32_e32 v25, v25, v37
	v_add_f32_e32 v26, v26, v38
	v_add_f32_e32 v27, v27, v39
	v_add_f32_e32 v28, v28, v40
	v_add_f32_e32 v29, v29, v41
	v_add_f32_e32 v30, v30, v42
	v_add_f32_e32 v31, v31, v43
	v_mov_b32_e32 v45, 0xff800000
	v_cmp_lt_u32_e32 vcc, 0, v7
	s_nop 1
	v_cndmask_b32_e32 v20, v45, v20, vcc
	v_cmp_ge_u32_e32 vcc, 0, v7
	s_nop 1
	v_cndmask_b32_e32 v28, v45, v28, vcc
	v_cmp_lt_u32_e32 vcc, 1, v7
	s_nop 1
	v_cndmask_b32_e32 v21, v45, v21, vcc
	v_cmp_ge_u32_e32 vcc, 1, v7
	s_nop 1
	v_cndmask_b32_e32 v29, v45, v29, vcc
	v_cmp_lt_u32_e32 vcc, 2, v7
	s_nop 1
	v_cndmask_b32_e32 v22, v45, v22, vcc
	v_cmp_ge_u32_e32 vcc, 2, v7
	s_nop 1
	v_cndmask_b32_e32 v30, v45, v30, vcc
	v_cmp_lt_u32_e32 vcc, 3, v7
	s_nop 1
	v_cndmask_b32_e32 v23, v45, v23, vcc
	v_cmp_ge_u32_e32 vcc, 3, v7
	s_nop 1
	v_cndmask_b32_e32 v31, v45, v31, vcc
	v_max3_f32 v46, v20, v24, v28
	v_max3_f32 v47, v21, v25, v29
	v_max3_f32 v48, v22, v26, v30
	v_max3_f32 v49, v23, v27, v31
	v_xor_b32_e32 v54, 32, v7
	v_lshlrev_b32_e32 v54, 2, v54
	ds_swizzle_b32 v50, v46 offset:0x41f
	ds_swizzle_b32 v51, v47 offset:0x41f
	ds_swizzle_b32 v52, v48 offset:0x41f
	ds_swizzle_b32 v53, v49 offset:0x41f
	s_waitcnt lgkmcnt(0)
	v_max_f32_e32 v46, v46, v50
	v_max_f32_e32 v47, v47, v51
	v_max_f32_e32 v48, v48, v52
	v_max_f32_e32 v49, v49, v53
	ds_swizzle_b32 v50, v46 offset:0x81f
	ds_swizzle_b32 v51, v47 offset:0x81f
	ds_swizzle_b32 v52, v48 offset:0x81f
	ds_swizzle_b32 v53, v49 offset:0x81f
	s_waitcnt lgkmcnt(0)
	v_max_f32_e32 v46, v46, v50
	v_max_f32_e32 v47, v47, v51
	v_max_f32_e32 v48, v48, v52
	v_max_f32_e32 v49, v49, v53
	ds_swizzle_b32 v50, v46 offset:0x101f
	ds_swizzle_b32 v51, v47 offset:0x101f
	ds_swizzle_b32 v52, v48 offset:0x101f
	ds_swizzle_b32 v53, v49 offset:0x101f
	s_waitcnt lgkmcnt(0)
	v_max_f32_e32 v46, v46, v50
	v_max_f32_e32 v47, v47, v51
	v_max_f32_e32 v48, v48, v52
	v_max_f32_e32 v49, v49, v53
	ds_swizzle_b32 v50, v46 offset:0x201f
	ds_swizzle_b32 v51, v47 offset:0x201f
	ds_swizzle_b32 v52, v48 offset:0x201f
	ds_swizzle_b32 v53, v49 offset:0x201f
	s_waitcnt lgkmcnt(0)
	v_max_f32_e32 v46, v46, v50
	v_max_f32_e32 v47, v47, v51
	v_max_f32_e32 v48, v48, v52
	v_max_f32_e32 v49, v49, v53
	ds_swizzle_b32 v50, v46 offset:0x401f
	ds_swizzle_b32 v51, v47 offset:0x401f
	ds_swizzle_b32 v52, v48 offset:0x401f
	ds_swizzle_b32 v53, v49 offset:0x401f
	s_waitcnt lgkmcnt(0)
	v_max_f32_e32 v46, v46, v50
	v_max_f32_e32 v47, v47, v51
	v_max_f32_e32 v48, v48, v52
	v_max_f32_e32 v49, v49, v53
	ds_bpermute_b32 v50, v54, v46
	ds_bpermute_b32 v51, v54, v47
	ds_bpermute_b32 v52, v54, v48
	ds_bpermute_b32 v53, v54, v49
	s_waitcnt lgkmcnt(0)
	v_max_f32_e32 v46, v46, v50
	v_max_f32_e32 v47, v47, v51
	v_max_f32_e32 v48, v48, v52
	v_max_f32_e32 v49, v49, v53
	s_waitcnt lgkmcnt(0)
	v_max_f32_e32 v46, s58, v46
	v_max_f32_e32 v47, s58, v47
	v_max_f32_e32 v48, s58, v48
	v_max_f32_e32 v49, s58, v49
	v_mov_b32_e32 v55, 0x3fb8aa3b
	v_sub_f32_e32 v20, v20, v46
	v_sub_f32_e32 v21, v21, v47
	v_sub_f32_e32 v22, v22, v48
	v_sub_f32_e32 v23, v23, v49
	v_sub_f32_e32 v24, v24, v46
	v_sub_f32_e32 v25, v25, v47
	v_sub_f32_e32 v26, v26, v48
	v_sub_f32_e32 v27, v27, v49
	v_sub_f32_e32 v28, v28, v46
	v_sub_f32_e32 v29, v29, v47
	v_sub_f32_e32 v30, v30, v48
	v_sub_f32_e32 v31, v31, v49
	v_mul_f32_e32 v20, v55, v20
	v_mul_f32_e32 v21, v55, v21
	v_mul_f32_e32 v22, v55, v22
	v_mul_f32_e32 v23, v55, v23
	v_mul_f32_e32 v24, v55, v24
	v_mul_f32_e32 v25, v55, v25
	v_mul_f32_e32 v26, v55, v26
	v_mul_f32_e32 v27, v55, v27
	v_mul_f32_e32 v28, v55, v28
	v_mul_f32_e32 v29, v55, v29
	v_mul_f32_e32 v30, v55, v30
	v_mul_f32_e32 v31, v55, v31
	v_exp_f32_e32 v20, v20
	v_exp_f32_e32 v21, v21
	v_exp_f32_e32 v22, v22
	v_exp_f32_e32 v23, v23
	v_exp_f32_e32 v24, v24
	v_exp_f32_e32 v25, v25
	v_exp_f32_e32 v26, v26
	v_exp_f32_e32 v27, v27
	v_exp_f32_e32 v28, v28
	v_exp_f32_e32 v29, v29
	v_exp_f32_e32 v30, v30
	v_exp_f32_e32 v31, v31
	s_nop 1
	v_add_f32_e32 v56, v20, v24
	v_add_f32_e32 v57, v21, v25
	v_add_f32_e32 v58, v22, v26
	v_add_f32_e32 v59, v23, v27
	v_add_f32_e32 v56, v56, v28
	v_add_f32_e32 v57, v57, v29
	v_add_f32_e32 v58, v58, v30
	v_add_f32_e32 v59, v59, v31
	ds_swizzle_b32 v50, v56 offset:0x41f
	ds_swizzle_b32 v51, v57 offset:0x41f
	ds_swizzle_b32 v52, v58 offset:0x41f
	ds_swizzle_b32 v53, v59 offset:0x41f
	s_waitcnt lgkmcnt(0)
	v_add_f32_e32 v56, v56, v50
	v_add_f32_e32 v57, v57, v51
	v_add_f32_e32 v58, v58, v52
	v_add_f32_e32 v59, v59, v53
	ds_swizzle_b32 v50, v56 offset:0x81f
	ds_swizzle_b32 v51, v57 offset:0x81f
	ds_swizzle_b32 v52, v58 offset:0x81f
	ds_swizzle_b32 v53, v59 offset:0x81f
	s_waitcnt lgkmcnt(0)
	v_add_f32_e32 v56, v56, v50
	v_add_f32_e32 v57, v57, v51
	v_add_f32_e32 v58, v58, v52
	v_add_f32_e32 v59, v59, v53
	ds_swizzle_b32 v50, v56 offset:0x101f
	ds_swizzle_b32 v51, v57 offset:0x101f
	ds_swizzle_b32 v52, v58 offset:0x101f
	ds_swizzle_b32 v53, v59 offset:0x101f
	s_waitcnt lgkmcnt(0)
	v_add_f32_e32 v56, v56, v50
	v_add_f32_e32 v57, v57, v51
	v_add_f32_e32 v58, v58, v52
	v_add_f32_e32 v59, v59, v53
	ds_swizzle_b32 v50, v56 offset:0x201f
	ds_swizzle_b32 v51, v57 offset:0x201f
	ds_swizzle_b32 v52, v58 offset:0x201f
	ds_swizzle_b32 v53, v59 offset:0x201f
	s_waitcnt lgkmcnt(0)
	v_add_f32_e32 v56, v56, v50
	v_add_f32_e32 v57, v57, v51
	v_add_f32_e32 v58, v58, v52
	v_add_f32_e32 v59, v59, v53
	ds_swizzle_b32 v50, v56 offset:0x401f
	ds_swizzle_b32 v51, v57 offset:0x401f
	ds_swizzle_b32 v52, v58 offset:0x401f
	ds_swizzle_b32 v53, v59 offset:0x401f
	s_waitcnt lgkmcnt(0)
	v_add_f32_e32 v56, v56, v50
	v_add_f32_e32 v57, v57, v51
	v_add_f32_e32 v58, v58, v52
	v_add_f32_e32 v59, v59, v53
	ds_bpermute_b32 v50, v54, v56
	ds_bpermute_b32 v51, v54, v57
	ds_bpermute_b32 v52, v54, v58
	ds_bpermute_b32 v53, v54, v59
	s_waitcnt lgkmcnt(0)
	v_add_f32_e32 v56, v56, v50
	v_add_f32_e32 v57, v57, v51
	v_add_f32_e32 v58, v58, v52
	v_add_f32_e32 v59, v59, v53
	v_sub_f32_e32 v60, s58, v46
	v_sub_f32_e32 v61, s58, v47
	v_sub_f32_e32 v62, s58, v48
	v_sub_f32_e32 v63, s58, v49
	v_mul_f32_e32 v60, v55, v60
	v_mul_f32_e32 v61, v55, v61
	v_mul_f32_e32 v62, v55, v62
	v_mul_f32_e32 v63, v55, v63
	v_exp_f32_e32 v60, v60
	v_exp_f32_e32 v61, v61
	v_exp_f32_e32 v62, v62
	v_exp_f32_e32 v63, v63
	s_nop 1
	v_add_f32_e32 v56, v56, v60
	v_add_f32_e32 v57, v57, v61
	v_add_f32_e32 v58, v58, v62
	v_add_f32_e32 v59, v59, v63
	v_rcp_f32_e32 v60, v56
	v_rcp_f32_e32 v61, v57
	v_rcp_f32_e32 v62, v58
	v_rcp_f32_e32 v63, v59
	s_nop 1
	v_fma_f32 v50, -v56, v60, 1.0
	v_fma_f32 v51, -v57, v61, 1.0
	v_fma_f32 v52, -v58, v62, 1.0
	v_fma_f32 v53, -v59, v63, 1.0
	v_fma_f32 v60, v50, v60, v60
	v_fma_f32 v61, v51, v61, v61
	v_fma_f32 v62, v52, v62, v62
	v_fma_f32 v63, v53, v63, v63
	v_mul_f32_e32 v20, v20, v60
	v_mul_f32_e32 v21, v21, v61
	v_mul_f32_e32 v22, v22, v62
	v_mul_f32_e32 v23, v23, v63
	v_mul_f32_e32 v24, v24, v60
	v_mul_f32_e32 v25, v25, v61
	v_mul_f32_e32 v26, v26, v62
	v_mul_f32_e32 v27, v27, v63
	v_mul_f32_e32 v28, v28, v60
	v_mul_f32_e32 v29, v29, v61
	v_mul_f32_e32 v30, v30, v62
	v_mul_f32_e32 v31, v31, v63
	v_add_u32_e32 v17, 0x400, v17
	ds_write_b128 v17, v[20:23]
	ds_write_b128 v17, v[24:27] offset:1024
	ds_write_b128 v17, v[28:31] offset:2048
	s_waitcnt lgkmcnt(0)
	v_lshlrev_b32_e32 v19, 2, v7
	v_add_u32_e32 v19, 0x9000, v19
	s_add_i32 s2, s59, 0x400
	v_mov_b32_e32 v3, s2
	v_mov_b32_e32 v4, 0
	v_mov_b32_e32 v5, 0
	v_mov_b32_e32 v6, 0
	v_mov_b32_e32 v8, 0
	ds_read_b128 v[20:23], v3 offset:0
	ds_read_b32 v32, v19 offset:0
	ds_read_b128 v[24:27], v3 offset:16
	ds_read_b32 v33, v19 offset:256
	ds_read_b128 v[28:31], v3 offset:32
	ds_read_b32 v34, v19 offset:512
	ds_read_b128 v[36:39], v3 offset:48
	ds_read_b32 v48, v19 offset:768
	ds_read_b128 v[40:43], v3 offset:64
	ds_read_b32 v49, v19 offset:1024
	ds_read_b128 v[44:47], v3 offset:80
	ds_read_b32 v50, v19 offset:1280
	s_waitcnt lgkmcnt(10)
	v_fmac_f32_e32 v4, v20, v32
	v_fmac_f32_e32 v5, v21, v32
	v_fmac_f32_e32 v6, v22, v32
	v_fmac_f32_e32 v8, v23, v32
	s_waitcnt lgkmcnt(8)
	v_fmac_f32_e32 v4, v24, v33
	v_fmac_f32_e32 v5, v25, v33
	v_fmac_f32_e32 v6, v26, v33
	v_fmac_f32_e32 v8, v27, v33
	s_waitcnt lgkmcnt(6)
	v_fmac_f32_e32 v4, v28, v34
	v_fmac_f32_e32 v5, v29, v34
	v_fmac_f32_e32 v6, v30, v34
	v_fmac_f32_e32 v8, v31, v34
	ds_read_b128 v[20:23], v3 offset:96
	ds_read_b32 v32, v19 offset:1536
	ds_read_b128 v[24:27], v3 offset:112
	ds_read_b32 v33, v19 offset:1792
	ds_read_b128 v[28:31], v3 offset:128
	ds_read_b32 v34, v19 offset:2048
	s_waitcnt lgkmcnt(10)
	v_fmac_f32_e32 v4, v36, v48
	v_fmac_f32_e32 v5, v37, v48
	v_fmac_f32_e32 v6, v38, v48
	v_fmac_f32_e32 v8, v39, v48
	s_waitcnt lgkmcnt(8)
	v_fmac_f32_e32 v4, v40, v49
	v_fmac_f32_e32 v5, v41, v49
	v_fmac_f32_e32 v6, v42, v49
	v_fmac_f32_e32 v8, v43, v49
	s_waitcnt lgkmcnt(6)
	v_fmac_f32_e32 v4, v44, v50
	v_fmac_f32_e32 v5, v45, v50
	v_fmac_f32_e32 v6, v46, v50
	v_fmac_f32_e32 v8, v47, v50
	ds_read_b128 v[36:39], v3 offset:144
	ds_read_b32 v48, v19 offset:2304
	ds_read_b128 v[40:43], v3 offset:160
	ds_read_b32 v49, v19 offset:2560
	ds_read_b128 v[44:47], v3 offset:176
	ds_read_b32 v50, v19 offset:2816
	s_waitcnt lgkmcnt(10)
	v_fmac_f32_e32 v4, v20, v32
	v_fmac_f32_e32 v5, v21, v32
	v_fmac_f32_e32 v6, v22, v32
	v_fmac_f32_e32 v8, v23, v32
	s_waitcnt lgkmcnt(8)
	v_fmac_f32_e32 v4, v24, v33
	v_fmac_f32_e32 v5, v25, v33
	v_fmac_f32_e32 v6, v26, v33
	v_fmac_f32_e32 v8, v27, v33
	s_waitcnt lgkmcnt(6)
	v_fmac_f32_e32 v4, v28, v34
	v_fmac_f32_e32 v5, v29, v34
	v_fmac_f32_e32 v6, v30, v34
	v_fmac_f32_e32 v8, v31, v34
	ds_read_b128 v[20:23], v3 offset:192
	ds_read_b32 v32, v19 offset:3072
	ds_read_b128 v[24:27], v3 offset:208
	ds_read_b32 v33, v19 offset:3328
	ds_read_b128 v[28:31], v3 offset:224
	ds_read_b32 v34, v19 offset:3584
	s_waitcnt lgkmcnt(10)
	v_fmac_f32_e32 v4, v36, v48
	v_fmac_f32_e32 v5, v37, v48
	v_fmac_f32_e32 v6, v38, v48
	v_fmac_f32_e32 v8, v39, v48
	s_waitcnt lgkmcnt(8)
	v_fmac_f32_e32 v4, v40, v49
	v_fmac_f32_e32 v5, v41, v49
	v_fmac_f32_e32 v6, v42, v49
	v_fmac_f32_e32 v8, v43, v49
	s_waitcnt lgkmcnt(6)
	v_fmac_f32_e32 v4, v44, v50
	v_fmac_f32_e32 v5, v45, v50
	v_fmac_f32_e32 v6, v46, v50
	v_fmac_f32_e32 v8, v47, v50
	ds_read_b128 v[36:39], v3 offset:240
	ds_read_b32 v48, v19 offset:3840
	ds_read_b128 v[40:43], v3 offset:256
	ds_read_b32 v49, v19 offset:4096
	ds_read_b128 v[44:47], v3 offset:272
	ds_read_b32 v50, v19 offset:4352
	s_waitcnt lgkmcnt(10)
	v_fmac_f32_e32 v4, v20, v32
	v_fmac_f32_e32 v5, v21, v32
	v_fmac_f32_e32 v6, v22, v32
	v_fmac_f32_e32 v8, v23, v32
	s_waitcnt lgkmcnt(8)
	v_fmac_f32_e32 v4, v24, v33
	v_fmac_f32_e32 v5, v25, v33
	v_fmac_f32_e32 v6, v26, v33
	v_fmac_f32_e32 v8, v27, v33
	s_waitcnt lgkmcnt(6)
	v_fmac_f32_e32 v4, v28, v34
	v_fmac_f32_e32 v5, v29, v34
	v_fmac_f32_e32 v6, v30, v34
	v_fmac_f32_e32 v8, v31, v34
	ds_read_b128 v[20:23], v3 offset:288
	ds_read_b32 v32, v19 offset:4608
	ds_read_b128 v[24:27], v3 offset:304
	ds_read_b32 v33, v19 offset:4864
	ds_read_b128 v[28:31], v3 offset:320
	ds_read_b32 v34, v19 offset:5120
	s_waitcnt lgkmcnt(10)
	v_fmac_f32_e32 v4, v36, v48
	v_fmac_f32_e32 v5, v37, v48
	v_fmac_f32_e32 v6, v38, v48
	v_fmac_f32_e32 v8, v39, v48
	s_waitcnt lgkmcnt(8)
	v_fmac_f32_e32 v4, v40, v49
	v_fmac_f32_e32 v5, v41, v49
	v_fmac_f32_e32 v6, v42, v49
	v_fmac_f32_e32 v8, v43, v49
	s_waitcnt lgkmcnt(6)
	v_fmac_f32_e32 v4, v44, v50
	v_fmac_f32_e32 v5, v45, v50
	v_fmac_f32_e32 v6, v46, v50
	v_fmac_f32_e32 v8, v47, v50
	ds_read_b128 v[36:39], v3 offset:336
	ds_read_b32 v48, v19 offset:5376
	ds_read_b128 v[40:43], v3 offset:352
	ds_read_b32 v49, v19 offset:5632
	ds_read_b128 v[44:47], v3 offset:368
	ds_read_b32 v50, v19 offset:5888
	s_waitcnt lgkmcnt(10)
	v_fmac_f32_e32 v4, v20, v32
	v_fmac_f32_e32 v5, v21, v32
	v_fmac_f32_e32 v6, v22, v32
	v_fmac_f32_e32 v8, v23, v32
	s_waitcnt lgkmcnt(8)
	v_fmac_f32_e32 v4, v24, v33
	v_fmac_f32_e32 v5, v25, v33
	v_fmac_f32_e32 v6, v26, v33
	v_fmac_f32_e32 v8, v27, v33
	s_waitcnt lgkmcnt(6)
	v_fmac_f32_e32 v4, v28, v34
	v_fmac_f32_e32 v5, v29, v34
	v_fmac_f32_e32 v6, v30, v34
	v_fmac_f32_e32 v8, v31, v34
	ds_read_b128 v[20:23], v3 offset:384
	ds_read_b32 v32, v19 offset:6144
	ds_read_b128 v[24:27], v3 offset:400
	ds_read_b32 v33, v19 offset:6400
	ds_read_b128 v[28:31], v3 offset:416
	ds_read_b32 v34, v19 offset:6656
	s_waitcnt lgkmcnt(10)
	v_fmac_f32_e32 v4, v36, v48
	v_fmac_f32_e32 v5, v37, v48
	v_fmac_f32_e32 v6, v38, v48
	v_fmac_f32_e32 v8, v39, v48
	s_waitcnt lgkmcnt(8)
	v_fmac_f32_e32 v4, v40, v49
	v_fmac_f32_e32 v5, v41, v49
	v_fmac_f32_e32 v6, v42, v49
	v_fmac_f32_e32 v8, v43, v49
	s_waitcnt lgkmcnt(6)
	v_fmac_f32_e32 v4, v44, v50
	v_fmac_f32_e32 v5, v45, v50
	v_fmac_f32_e32 v6, v46, v50
	v_fmac_f32_e32 v8, v47, v50
	ds_read_b128 v[36:39], v3 offset:432
	ds_read_b32 v48, v19 offset:6912
	ds_read_b128 v[40:43], v3 offset:448
	ds_read_b32 v49, v19 offset:7168
	ds_read_b128 v[44:47], v3 offset:464
	ds_read_b32 v50, v19 offset:7424
	s_waitcnt lgkmcnt(10)
	v_fmac_f32_e32 v4, v20, v32
	v_fmac_f32_e32 v5, v21, v32
	v_fmac_f32_e32 v6, v22, v32
	v_fmac_f32_e32 v8, v23, v32
	s_waitcnt lgkmcnt(8)
	v_fmac_f32_e32 v4, v24, v33
	v_fmac_f32_e32 v5, v25, v33
	v_fmac_f32_e32 v6, v26, v33
	v_fmac_f32_e32 v8, v27, v33
	s_waitcnt lgkmcnt(6)
	v_fmac_f32_e32 v4, v28, v34
	v_fmac_f32_e32 v5, v29, v34
	v_fmac_f32_e32 v6, v30, v34
	v_fmac_f32_e32 v8, v31, v34
	ds_read_b128 v[20:23], v3 offset:480
	ds_read_b32 v32, v19 offset:7680
	ds_read_b128 v[24:27], v3 offset:496
	ds_read_b32 v33, v19 offset:7936
	ds_read_b128 v[28:31], v3 offset:512
	ds_read_b32 v34, v19 offset:8192
	s_waitcnt lgkmcnt(10)
	v_fmac_f32_e32 v4, v36, v48
	v_fmac_f32_e32 v5, v37, v48
	v_fmac_f32_e32 v6, v38, v48
	v_fmac_f32_e32 v8, v39, v48
	s_waitcnt lgkmcnt(8)
	v_fmac_f32_e32 v4, v40, v49
	v_fmac_f32_e32 v5, v41, v49
	v_fmac_f32_e32 v6, v42, v49
	v_fmac_f32_e32 v8, v43, v49
	s_waitcnt lgkmcnt(6)
	v_fmac_f32_e32 v4, v44, v50
	v_fmac_f32_e32 v5, v45, v50
	v_fmac_f32_e32 v6, v46, v50
	v_fmac_f32_e32 v8, v47, v50
	ds_read_b128 v[36:39], v3 offset:528
	ds_read_b32 v48, v19 offset:8448
	ds_read_b128 v[40:43], v3 offset:544
	ds_read_b32 v49, v19 offset:8704
	ds_read_b128 v[44:47], v3 offset:560
	ds_read_b32 v50, v19 offset:8960
	s_waitcnt lgkmcnt(10)
	v_fmac_f32_e32 v4, v20, v32
	v_fmac_f32_e32 v5, v21, v32
	v_fmac_f32_e32 v6, v22, v32
	v_fmac_f32_e32 v8, v23, v32
	s_waitcnt lgkmcnt(8)
	v_fmac_f32_e32 v4, v24, v33
	v_fmac_f32_e32 v5, v25, v33
	v_fmac_f32_e32 v6, v26, v33
	v_fmac_f32_e32 v8, v27, v33
	s_waitcnt lgkmcnt(6)
	v_fmac_f32_e32 v4, v28, v34
	v_fmac_f32_e32 v5, v29, v34
	v_fmac_f32_e32 v6, v30, v34
	v_fmac_f32_e32 v8, v31, v34
	ds_read_b128 v[20:23], v3 offset:576
	ds_read_b32 v32, v19 offset:9216
	ds_read_b128 v[24:27], v3 offset:592
	ds_read_b32 v33, v19 offset:9472
	ds_read_b128 v[28:31], v3 offset:608
	ds_read_b32 v34, v19 offset:9728
	s_waitcnt lgkmcnt(10)
	v_fmac_f32_e32 v4, v36, v48
	v_fmac_f32_e32 v5, v37, v48
	v_fmac_f32_e32 v6, v38, v48
	v_fmac_f32_e32 v8, v39, v48
	s_waitcnt lgkmcnt(8)
	v_fmac_f32_e32 v4, v40, v49
	v_fmac_f32_e32 v5, v41, v49
	v_fmac_f32_e32 v6, v42, v49
	v_fmac_f32_e32 v8, v43, v49
	s_waitcnt lgkmcnt(6)
	v_fmac_f32_e32 v4, v44, v50
	v_fmac_f32_e32 v5, v45, v50
	v_fmac_f32_e32 v6, v46, v50
	v_fmac_f32_e32 v8, v47, v50
	ds_read_b128 v[36:39], v3 offset:624
	ds_read_b32 v48, v19 offset:9984
	ds_read_b128 v[40:43], v3 offset:640
	ds_read_b32 v49, v19 offset:10240
	ds_read_b128 v[44:47], v3 offset:656
	ds_read_b32 v50, v19 offset:10496
	s_waitcnt lgkmcnt(10)
	v_fmac_f32_e32 v4, v20, v32
	v_fmac_f32_e32 v5, v21, v32
	v_fmac_f32_e32 v6, v22, v32
	v_fmac_f32_e32 v8, v23, v32
	s_waitcnt lgkmcnt(8)
	v_fmac_f32_e32 v4, v24, v33
	v_fmac_f32_e32 v5, v25, v33
	v_fmac_f32_e32 v6, v26, v33
	v_fmac_f32_e32 v8, v27, v33
	s_waitcnt lgkmcnt(6)
	v_fmac_f32_e32 v4, v28, v34
	v_fmac_f32_e32 v5, v29, v34
	v_fmac_f32_e32 v6, v30, v34
	v_fmac_f32_e32 v8, v31, v34
	ds_read_b128 v[20:23], v3 offset:672
	ds_read_b32 v32, v19 offset:10752
	ds_read_b128 v[24:27], v3 offset:688
	ds_read_b32 v33, v19 offset:11008
	ds_read_b128 v[28:31], v3 offset:704
	ds_read_b32 v34, v19 offset:11264
	s_waitcnt lgkmcnt(10)
	v_fmac_f32_e32 v4, v36, v48
	v_fmac_f32_e32 v5, v37, v48
	v_fmac_f32_e32 v6, v38, v48
	v_fmac_f32_e32 v8, v39, v48
	s_waitcnt lgkmcnt(8)
	v_fmac_f32_e32 v4, v40, v49
	v_fmac_f32_e32 v5, v41, v49
	v_fmac_f32_e32 v6, v42, v49
	v_fmac_f32_e32 v8, v43, v49
	s_waitcnt lgkmcnt(6)
	v_fmac_f32_e32 v4, v44, v50
	v_fmac_f32_e32 v5, v45, v50
	v_fmac_f32_e32 v6, v46, v50
	v_fmac_f32_e32 v8, v47, v50
	ds_read_b128 v[36:39], v3 offset:720
	ds_read_b32 v48, v19 offset:11520
	ds_read_b128 v[40:43], v3 offset:736
	ds_read_b32 v49, v19 offset:11776
	ds_read_b128 v[44:47], v3 offset:752
	ds_read_b32 v50, v19 offset:12032
	s_waitcnt lgkmcnt(10)
	v_fmac_f32_e32 v4, v20, v32
	v_fmac_f32_e32 v5, v21, v32
	v_fmac_f32_e32 v6, v22, v32
	v_fmac_f32_e32 v8, v23, v32
	s_waitcnt lgkmcnt(8)
	v_fmac_f32_e32 v4, v24, v33
	v_fmac_f32_e32 v5, v25, v33
	v_fmac_f32_e32 v6, v26, v33
	v_fmac_f32_e32 v8, v27, v33
	s_waitcnt lgkmcnt(6)
	v_fmac_f32_e32 v4, v28, v34
	v_fmac_f32_e32 v5, v29, v34
	v_fmac_f32_e32 v6, v30, v34
	v_fmac_f32_e32 v8, v31, v34
	ds_read_b128 v[20:23], v3 offset:768
	ds_read_b32 v32, v19 offset:12288
	ds_read_b128 v[24:27], v3 offset:784
	ds_read_b32 v33, v19 offset:12544
	ds_read_b128 v[28:31], v3 offset:800
	ds_read_b32 v34, v19 offset:12800
	s_waitcnt lgkmcnt(10)
	v_fmac_f32_e32 v4, v36, v48
	v_fmac_f32_e32 v5, v37, v48
	v_fmac_f32_e32 v6, v38, v48
	v_fmac_f32_e32 v8, v39, v48
	s_waitcnt lgkmcnt(8)
	v_fmac_f32_e32 v4, v40, v49
	v_fmac_f32_e32 v5, v41, v49
	v_fmac_f32_e32 v6, v42, v49
	v_fmac_f32_e32 v8, v43, v49
	s_waitcnt lgkmcnt(6)
	v_fmac_f32_e32 v4, v44, v50
	v_fmac_f32_e32 v5, v45, v50
	v_fmac_f32_e32 v6, v46, v50
	v_fmac_f32_e32 v8, v47, v50
	ds_read_b128 v[36:39], v3 offset:816
	ds_read_b32 v48, v19 offset:13056
	ds_read_b128 v[40:43], v3 offset:832
	ds_read_b32 v49, v19 offset:13312
	ds_read_b128 v[44:47], v3 offset:848
	ds_read_b32 v50, v19 offset:13568
	s_waitcnt lgkmcnt(10)
	v_fmac_f32_e32 v4, v20, v32
	v_fmac_f32_e32 v5, v21, v32
	v_fmac_f32_e32 v6, v22, v32
	v_fmac_f32_e32 v8, v23, v32
	s_waitcnt lgkmcnt(8)
	v_fmac_f32_e32 v4, v24, v33
	v_fmac_f32_e32 v5, v25, v33
	v_fmac_f32_e32 v6, v26, v33
	v_fmac_f32_e32 v8, v27, v33
	s_waitcnt lgkmcnt(6)
	v_fmac_f32_e32 v4, v28, v34
	v_fmac_f32_e32 v5, v29, v34
	v_fmac_f32_e32 v6, v30, v34
	v_fmac_f32_e32 v8, v31, v34
	ds_read_b128 v[20:23], v3 offset:864
	ds_read_b32 v32, v19 offset:13824
	ds_read_b128 v[24:27], v3 offset:880
	ds_read_b32 v33, v19 offset:14080
	ds_read_b128 v[28:31], v3 offset:896
	ds_read_b32 v34, v19 offset:14336
	s_waitcnt lgkmcnt(10)
	v_fmac_f32_e32 v4, v36, v48
	v_fmac_f32_e32 v5, v37, v48
	v_fmac_f32_e32 v6, v38, v48
	v_fmac_f32_e32 v8, v39, v48
	s_waitcnt lgkmcnt(8)
	v_fmac_f32_e32 v4, v40, v49
	v_fmac_f32_e32 v5, v41, v49
	v_fmac_f32_e32 v6, v42, v49
	v_fmac_f32_e32 v8, v43, v49
	s_waitcnt lgkmcnt(6)
	v_fmac_f32_e32 v4, v44, v50
	v_fmac_f32_e32 v5, v45, v50
	v_fmac_f32_e32 v6, v46, v50
	v_fmac_f32_e32 v8, v47, v50
	ds_read_b128 v[36:39], v3 offset:912
	ds_read_b32 v48, v19 offset:14592
	ds_read_b128 v[40:43], v3 offset:928
	ds_read_b32 v49, v19 offset:14848
	ds_read_b128 v[44:47], v3 offset:944
	ds_read_b32 v50, v19 offset:15104
	s_waitcnt lgkmcnt(10)
	v_fmac_f32_e32 v4, v20, v32
	v_fmac_f32_e32 v5, v21, v32
	v_fmac_f32_e32 v6, v22, v32
	v_fmac_f32_e32 v8, v23, v32
	s_waitcnt lgkmcnt(8)
	v_fmac_f32_e32 v4, v24, v33
	v_fmac_f32_e32 v5, v25, v33
	v_fmac_f32_e32 v6, v26, v33
	v_fmac_f32_e32 v8, v27, v33
	s_waitcnt lgkmcnt(6)
	v_fmac_f32_e32 v4, v28, v34
	v_fmac_f32_e32 v5, v29, v34
	v_fmac_f32_e32 v6, v30, v34
	v_fmac_f32_e32 v8, v31, v34
	ds_read_b128 v[20:23], v3 offset:960
	ds_read_b32 v32, v19 offset:15360
	ds_read_b128 v[24:27], v3 offset:976
	ds_read_b32 v33, v19 offset:15616
	ds_read_b128 v[28:31], v3 offset:992
	ds_read_b32 v34, v19 offset:15872
	s_waitcnt lgkmcnt(10)
	v_fmac_f32_e32 v4, v36, v48
	v_fmac_f32_e32 v5, v37, v48
	v_fmac_f32_e32 v6, v38, v48
	v_fmac_f32_e32 v8, v39, v48
	s_waitcnt lgkmcnt(8)
	v_fmac_f32_e32 v4, v40, v49
	v_fmac_f32_e32 v5, v41, v49
	v_fmac_f32_e32 v6, v42, v49
	v_fmac_f32_e32 v8, v43, v49
	s_waitcnt lgkmcnt(6)
	v_fmac_f32_e32 v4, v44, v50
	v_fmac_f32_e32 v5, v45, v50
	v_fmac_f32_e32 v6, v46, v50
	v_fmac_f32_e32 v8, v47, v50
	ds_read_b128 v[36:39], v3 offset:1008
	ds_read_b32 v48, v19 offset:16128
	ds_read_b128 v[40:43], v3 offset:1024
	ds_read_b32 v49, v19 offset:16384
	ds_read_b128 v[44:47], v3 offset:1040
	ds_read_b32 v50, v19 offset:16640
	s_waitcnt lgkmcnt(10)
	v_fmac_f32_e32 v4, v20, v32
	v_fmac_f32_e32 v5, v21, v32
	v_fmac_f32_e32 v6, v22, v32
	v_fmac_f32_e32 v8, v23, v32
	s_waitcnt lgkmcnt(8)
	v_fmac_f32_e32 v4, v24, v33
	v_fmac_f32_e32 v5, v25, v33
	v_fmac_f32_e32 v6, v26, v33
	v_fmac_f32_e32 v8, v27, v33
	s_waitcnt lgkmcnt(6)
	v_fmac_f32_e32 v4, v28, v34
	v_fmac_f32_e32 v5, v29, v34
	v_fmac_f32_e32 v6, v30, v34
	v_fmac_f32_e32 v8, v31, v34
	ds_read_b128 v[20:23], v3 offset:1056
	ds_read_b32 v32, v19 offset:16896
	ds_read_b128 v[24:27], v3 offset:1072
	ds_read_b32 v33, v19 offset:17152
	ds_read_b128 v[28:31], v3 offset:1088
	ds_read_b32 v34, v19 offset:17408
	s_waitcnt lgkmcnt(10)
	v_fmac_f32_e32 v4, v36, v48
	v_fmac_f32_e32 v5, v37, v48
	v_fmac_f32_e32 v6, v38, v48
	v_fmac_f32_e32 v8, v39, v48
	s_waitcnt lgkmcnt(8)
	v_fmac_f32_e32 v4, v40, v49
	v_fmac_f32_e32 v5, v41, v49
	v_fmac_f32_e32 v6, v42, v49
	v_fmac_f32_e32 v8, v43, v49
	s_waitcnt lgkmcnt(6)
	v_fmac_f32_e32 v4, v44, v50
	v_fmac_f32_e32 v5, v45, v50
	v_fmac_f32_e32 v6, v46, v50
	v_fmac_f32_e32 v8, v47, v50
	ds_read_b128 v[36:39], v3 offset:1104
	ds_read_b32 v48, v19 offset:17664
	ds_read_b128 v[40:43], v3 offset:1120
	ds_read_b32 v49, v19 offset:17920
	ds_read_b128 v[44:47], v3 offset:1136
	ds_read_b32 v50, v19 offset:18176
	s_waitcnt lgkmcnt(10)
	v_fmac_f32_e32 v4, v20, v32
	v_fmac_f32_e32 v5, v21, v32
	v_fmac_f32_e32 v6, v22, v32
	v_fmac_f32_e32 v8, v23, v32
	s_waitcnt lgkmcnt(8)
	v_fmac_f32_e32 v4, v24, v33
	v_fmac_f32_e32 v5, v25, v33
	v_fmac_f32_e32 v6, v26, v33
	v_fmac_f32_e32 v8, v27, v33
	s_waitcnt lgkmcnt(6)
	v_fmac_f32_e32 v4, v28, v34
	v_fmac_f32_e32 v5, v29, v34
	v_fmac_f32_e32 v6, v30, v34
	v_fmac_f32_e32 v8, v31, v34
	ds_read_b128 v[20:23], v3 offset:1152
	ds_read_b32 v32, v19 offset:18432
	ds_read_b128 v[24:27], v3 offset:1168
	ds_read_b32 v33, v19 offset:18688
	ds_read_b128 v[28:31], v3 offset:1184
	ds_read_b32 v34, v19 offset:18944
	s_waitcnt lgkmcnt(10)
	v_fmac_f32_e32 v4, v36, v48
	v_fmac_f32_e32 v5, v37, v48
	v_fmac_f32_e32 v6, v38, v48
	v_fmac_f32_e32 v8, v39, v48
	s_waitcnt lgkmcnt(8)
	v_fmac_f32_e32 v4, v40, v49
	v_fmac_f32_e32 v5, v41, v49
	v_fmac_f32_e32 v6, v42, v49
	v_fmac_f32_e32 v8, v43, v49
	s_waitcnt lgkmcnt(6)
	v_fmac_f32_e32 v4, v44, v50
	v_fmac_f32_e32 v5, v45, v50
	v_fmac_f32_e32 v6, v46, v50
	v_fmac_f32_e32 v8, v47, v50
	ds_read_b128 v[36:39], v3 offset:1200
	ds_read_b32 v48, v19 offset:19200
	ds_read_b128 v[40:43], v3 offset:1216
	ds_read_b32 v49, v19 offset:19456
	ds_read_b128 v[44:47], v3 offset:1232
	ds_read_b32 v50, v19 offset:19712
	s_waitcnt lgkmcnt(10)
	v_fmac_f32_e32 v4, v20, v32
	v_fmac_f32_e32 v5, v21, v32
	v_fmac_f32_e32 v6, v22, v32
	v_fmac_f32_e32 v8, v23, v32
	s_waitcnt lgkmcnt(8)
	v_fmac_f32_e32 v4, v24, v33
	v_fmac_f32_e32 v5, v25, v33
	v_fmac_f32_e32 v6, v26, v33
	v_fmac_f32_e32 v8, v27, v33
	s_waitcnt lgkmcnt(6)
	v_fmac_f32_e32 v4, v28, v34
	v_fmac_f32_e32 v5, v29, v34
	v_fmac_f32_e32 v6, v30, v34
	v_fmac_f32_e32 v8, v31, v34
	ds_read_b128 v[20:23], v3 offset:1248
	ds_read_b32 v32, v19 offset:19968
	ds_read_b128 v[24:27], v3 offset:1264
	ds_read_b32 v33, v19 offset:20224
	ds_read_b128 v[28:31], v3 offset:1280
	ds_read_b32 v34, v19 offset:20480
	s_waitcnt lgkmcnt(10)
	v_fmac_f32_e32 v4, v36, v48
	v_fmac_f32_e32 v5, v37, v48
	v_fmac_f32_e32 v6, v38, v48
	v_fmac_f32_e32 v8, v39, v48
	s_waitcnt lgkmcnt(8)
	v_fmac_f32_e32 v4, v40, v49
	v_fmac_f32_e32 v5, v41, v49
	v_fmac_f32_e32 v6, v42, v49
	v_fmac_f32_e32 v8, v43, v49
	s_waitcnt lgkmcnt(6)
	v_fmac_f32_e32 v4, v44, v50
	v_fmac_f32_e32 v5, v45, v50
	v_fmac_f32_e32 v6, v46, v50
	v_fmac_f32_e32 v8, v47, v50
	ds_read_b128 v[36:39], v3 offset:1296
	ds_read_b32 v48, v19 offset:20736
	ds_read_b128 v[40:43], v3 offset:1312
	ds_read_b32 v49, v19 offset:20992
	ds_read_b128 v[44:47], v3 offset:1328
	ds_read_b32 v50, v19 offset:21248
	s_waitcnt lgkmcnt(10)
	v_fmac_f32_e32 v4, v20, v32
	v_fmac_f32_e32 v5, v21, v32
	v_fmac_f32_e32 v6, v22, v32
	v_fmac_f32_e32 v8, v23, v32
	s_waitcnt lgkmcnt(8)
	v_fmac_f32_e32 v4, v24, v33
	v_fmac_f32_e32 v5, v25, v33
	v_fmac_f32_e32 v6, v26, v33
	v_fmac_f32_e32 v8, v27, v33
	s_waitcnt lgkmcnt(6)
	v_fmac_f32_e32 v4, v28, v34
	v_fmac_f32_e32 v5, v29, v34
	v_fmac_f32_e32 v6, v30, v34
	v_fmac_f32_e32 v8, v31, v34
	ds_read_b128 v[20:23], v3 offset:1344
	ds_read_b32 v32, v19 offset:21504
	ds_read_b128 v[24:27], v3 offset:1360
	ds_read_b32 v33, v19 offset:21760
	ds_read_b128 v[28:31], v3 offset:1376
	ds_read_b32 v34, v19 offset:22016
	s_waitcnt lgkmcnt(10)
	v_fmac_f32_e32 v4, v36, v48
	v_fmac_f32_e32 v5, v37, v48
	v_fmac_f32_e32 v6, v38, v48
	v_fmac_f32_e32 v8, v39, v48
	s_waitcnt lgkmcnt(8)
	v_fmac_f32_e32 v4, v40, v49
	v_fmac_f32_e32 v5, v41, v49
	v_fmac_f32_e32 v6, v42, v49
	v_fmac_f32_e32 v8, v43, v49
	s_waitcnt lgkmcnt(6)
	v_fmac_f32_e32 v4, v44, v50
	v_fmac_f32_e32 v5, v45, v50
	v_fmac_f32_e32 v6, v46, v50
	v_fmac_f32_e32 v8, v47, v50
	ds_read_b128 v[36:39], v3 offset:1392
	ds_read_b32 v48, v19 offset:22272
	ds_read_b128 v[40:43], v3 offset:1408
	ds_read_b32 v49, v19 offset:22528
	ds_read_b128 v[44:47], v3 offset:1424
	ds_read_b32 v50, v19 offset:22784
	s_waitcnt lgkmcnt(10)
	v_fmac_f32_e32 v4, v20, v32
	v_fmac_f32_e32 v5, v21, v32
	v_fmac_f32_e32 v6, v22, v32
	v_fmac_f32_e32 v8, v23, v32
	s_waitcnt lgkmcnt(8)
	v_fmac_f32_e32 v4, v24, v33
	v_fmac_f32_e32 v5, v25, v33
	v_fmac_f32_e32 v6, v26, v33
	v_fmac_f32_e32 v8, v27, v33
	s_waitcnt lgkmcnt(6)
	v_fmac_f32_e32 v4, v28, v34
	v_fmac_f32_e32 v5, v29, v34
	v_fmac_f32_e32 v6, v30, v34
	v_fmac_f32_e32 v8, v31, v34
	ds_read_b128 v[20:23], v3 offset:1440
	ds_read_b32 v32, v19 offset:23040
	ds_read_b128 v[24:27], v3 offset:1456
	ds_read_b32 v33, v19 offset:23296
	ds_read_b128 v[28:31], v3 offset:1472
	ds_read_b32 v34, v19 offset:23552
	s_waitcnt lgkmcnt(10)
	v_fmac_f32_e32 v4, v36, v48
	v_fmac_f32_e32 v5, v37, v48
	v_fmac_f32_e32 v6, v38, v48
	v_fmac_f32_e32 v8, v39, v48
	s_waitcnt lgkmcnt(8)
	v_fmac_f32_e32 v4, v40, v49
	v_fmac_f32_e32 v5, v41, v49
	v_fmac_f32_e32 v6, v42, v49
	v_fmac_f32_e32 v8, v43, v49
	s_waitcnt lgkmcnt(6)
	v_fmac_f32_e32 v4, v44, v50
	v_fmac_f32_e32 v5, v45, v50
	v_fmac_f32_e32 v6, v46, v50
	v_fmac_f32_e32 v8, v47, v50
	ds_read_b128 v[36:39], v3 offset:1488
	ds_read_b32 v48, v19 offset:23808
	ds_read_b128 v[40:43], v3 offset:1504
	ds_read_b32 v49, v19 offset:24064
	ds_read_b128 v[44:47], v3 offset:1520
	ds_read_b32 v50, v19 offset:24320
	s_waitcnt lgkmcnt(10)
	v_fmac_f32_e32 v4, v20, v32
	v_fmac_f32_e32 v5, v21, v32
	v_fmac_f32_e32 v6, v22, v32
	v_fmac_f32_e32 v8, v23, v32
	s_waitcnt lgkmcnt(8)
	v_fmac_f32_e32 v4, v24, v33
	v_fmac_f32_e32 v5, v25, v33
	v_fmac_f32_e32 v6, v26, v33
	v_fmac_f32_e32 v8, v27, v33
	s_waitcnt lgkmcnt(6)
	v_fmac_f32_e32 v4, v28, v34
	v_fmac_f32_e32 v5, v29, v34
	v_fmac_f32_e32 v6, v30, v34
	v_fmac_f32_e32 v8, v31, v34
	ds_read_b128 v[20:23], v3 offset:1536
	ds_read_b32 v32, v19 offset:24576
	ds_read_b128 v[24:27], v3 offset:1552
	ds_read_b32 v33, v19 offset:24832
	ds_read_b128 v[28:31], v3 offset:1568
	ds_read_b32 v34, v19 offset:25088
	s_waitcnt lgkmcnt(10)
	v_fmac_f32_e32 v4, v36, v48
	v_fmac_f32_e32 v5, v37, v48
	v_fmac_f32_e32 v6, v38, v48
	v_fmac_f32_e32 v8, v39, v48
	s_waitcnt lgkmcnt(8)
	v_fmac_f32_e32 v4, v40, v49
	v_fmac_f32_e32 v5, v41, v49
	v_fmac_f32_e32 v6, v42, v49
	v_fmac_f32_e32 v8, v43, v49
	s_waitcnt lgkmcnt(6)
	v_fmac_f32_e32 v4, v44, v50
	v_fmac_f32_e32 v5, v45, v50
	v_fmac_f32_e32 v6, v46, v50
	v_fmac_f32_e32 v8, v47, v50
	ds_read_b128 v[36:39], v3 offset:1584
	ds_read_b32 v48, v19 offset:25344
	ds_read_b128 v[40:43], v3 offset:1600
	ds_read_b32 v49, v19 offset:25600
	ds_read_b128 v[44:47], v3 offset:1616
	ds_read_b32 v50, v19 offset:25856
	s_waitcnt lgkmcnt(10)
	v_fmac_f32_e32 v4, v20, v32
	v_fmac_f32_e32 v5, v21, v32
	v_fmac_f32_e32 v6, v22, v32
	v_fmac_f32_e32 v8, v23, v32
	s_waitcnt lgkmcnt(8)
	v_fmac_f32_e32 v4, v24, v33
	v_fmac_f32_e32 v5, v25, v33
	v_fmac_f32_e32 v6, v26, v33
	v_fmac_f32_e32 v8, v27, v33
	s_waitcnt lgkmcnt(6)
	v_fmac_f32_e32 v4, v28, v34
	v_fmac_f32_e32 v5, v29, v34
	v_fmac_f32_e32 v6, v30, v34
	v_fmac_f32_e32 v8, v31, v34
	ds_read_b128 v[20:23], v3 offset:1632
	ds_read_b32 v32, v19 offset:26112
	ds_read_b128 v[24:27], v3 offset:1648
	ds_read_b32 v33, v19 offset:26368
	ds_read_b128 v[28:31], v3 offset:1664
	ds_read_b32 v34, v19 offset:26624
	s_waitcnt lgkmcnt(10)
	v_fmac_f32_e32 v4, v36, v48
	v_fmac_f32_e32 v5, v37, v48
	v_fmac_f32_e32 v6, v38, v48
	v_fmac_f32_e32 v8, v39, v48
	s_waitcnt lgkmcnt(8)
	v_fmac_f32_e32 v4, v40, v49
	v_fmac_f32_e32 v5, v41, v49
	v_fmac_f32_e32 v6, v42, v49
	v_fmac_f32_e32 v8, v43, v49
	s_waitcnt lgkmcnt(6)
	v_fmac_f32_e32 v4, v44, v50
	v_fmac_f32_e32 v5, v45, v50
	v_fmac_f32_e32 v6, v46, v50
	v_fmac_f32_e32 v8, v47, v50
	ds_read_b128 v[36:39], v3 offset:1680
	ds_read_b32 v48, v19 offset:26880
	ds_read_b128 v[40:43], v3 offset:1696
	ds_read_b32 v49, v19 offset:27136
	ds_read_b128 v[44:47], v3 offset:1712
	ds_read_b32 v50, v19 offset:27392
	s_waitcnt lgkmcnt(10)
	v_fmac_f32_e32 v4, v20, v32
	v_fmac_f32_e32 v5, v21, v32
	v_fmac_f32_e32 v6, v22, v32
	v_fmac_f32_e32 v8, v23, v32
	s_waitcnt lgkmcnt(8)
	v_fmac_f32_e32 v4, v24, v33
	v_fmac_f32_e32 v5, v25, v33
	v_fmac_f32_e32 v6, v26, v33
	v_fmac_f32_e32 v8, v27, v33
	s_waitcnt lgkmcnt(6)
	v_fmac_f32_e32 v4, v28, v34
	v_fmac_f32_e32 v5, v29, v34
	v_fmac_f32_e32 v6, v30, v34
	v_fmac_f32_e32 v8, v31, v34
	ds_read_b128 v[20:23], v3 offset:1728
	ds_read_b32 v32, v19 offset:27648
	ds_read_b128 v[24:27], v3 offset:1744
	ds_read_b32 v33, v19 offset:27904
	ds_read_b128 v[28:31], v3 offset:1760
	ds_read_b32 v34, v19 offset:28160
	s_waitcnt lgkmcnt(10)
	v_fmac_f32_e32 v4, v36, v48
	v_fmac_f32_e32 v5, v37, v48
	v_fmac_f32_e32 v6, v38, v48
	v_fmac_f32_e32 v8, v39, v48
	s_waitcnt lgkmcnt(8)
	v_fmac_f32_e32 v4, v40, v49
	v_fmac_f32_e32 v5, v41, v49
	v_fmac_f32_e32 v6, v42, v49
	v_fmac_f32_e32 v8, v43, v49
	s_waitcnt lgkmcnt(6)
	v_fmac_f32_e32 v4, v44, v50
	v_fmac_f32_e32 v5, v45, v50
	v_fmac_f32_e32 v6, v46, v50
	v_fmac_f32_e32 v8, v47, v50
	ds_read_b128 v[36:39], v3 offset:1776
	ds_read_b32 v48, v19 offset:28416
	ds_read_b128 v[40:43], v3 offset:1792
	ds_read_b32 v49, v19 offset:28672
	ds_read_b128 v[44:47], v3 offset:1808
	ds_read_b32 v50, v19 offset:28928
	s_waitcnt lgkmcnt(10)
	v_fmac_f32_e32 v4, v20, v32
	v_fmac_f32_e32 v5, v21, v32
	v_fmac_f32_e32 v6, v22, v32
	v_fmac_f32_e32 v8, v23, v32
	s_waitcnt lgkmcnt(8)
	v_fmac_f32_e32 v4, v24, v33
	v_fmac_f32_e32 v5, v25, v33
	v_fmac_f32_e32 v6, v26, v33
	v_fmac_f32_e32 v8, v27, v33
	s_waitcnt lgkmcnt(6)
	v_fmac_f32_e32 v4, v28, v34
	v_fmac_f32_e32 v5, v29, v34
	v_fmac_f32_e32 v6, v30, v34
	v_fmac_f32_e32 v8, v31, v34
	ds_read_b128 v[20:23], v3 offset:1824
	ds_read_b32 v32, v19 offset:29184
	ds_read_b128 v[24:27], v3 offset:1840
	ds_read_b32 v33, v19 offset:29440
	ds_read_b128 v[28:31], v3 offset:1856
	ds_read_b32 v34, v19 offset:29696
	s_waitcnt lgkmcnt(10)
	v_fmac_f32_e32 v4, v36, v48
	v_fmac_f32_e32 v5, v37, v48
	v_fmac_f32_e32 v6, v38, v48
	v_fmac_f32_e32 v8, v39, v48
	s_waitcnt lgkmcnt(8)
	v_fmac_f32_e32 v4, v40, v49
	v_fmac_f32_e32 v5, v41, v49
	v_fmac_f32_e32 v6, v42, v49
	v_fmac_f32_e32 v8, v43, v49
	s_waitcnt lgkmcnt(6)
	v_fmac_f32_e32 v4, v44, v50
	v_fmac_f32_e32 v5, v45, v50
	v_fmac_f32_e32 v6, v46, v50
	v_fmac_f32_e32 v8, v47, v50
	ds_read_b128 v[36:39], v3 offset:1872
	ds_read_b32 v48, v19 offset:29952
	ds_read_b128 v[40:43], v3 offset:1888
	ds_read_b32 v49, v19 offset:30208
	ds_read_b128 v[44:47], v3 offset:1904
	ds_read_b32 v50, v19 offset:30464
	s_waitcnt lgkmcnt(10)
	v_fmac_f32_e32 v4, v20, v32
	v_fmac_f32_e32 v5, v21, v32
	v_fmac_f32_e32 v6, v22, v32
	v_fmac_f32_e32 v8, v23, v32
	s_waitcnt lgkmcnt(8)
	v_fmac_f32_e32 v4, v24, v33
	v_fmac_f32_e32 v5, v25, v33
	v_fmac_f32_e32 v6, v26, v33
	v_fmac_f32_e32 v8, v27, v33
	s_waitcnt lgkmcnt(6)
	v_fmac_f32_e32 v4, v28, v34
	v_fmac_f32_e32 v5, v29, v34
	v_fmac_f32_e32 v6, v30, v34
	v_fmac_f32_e32 v8, v31, v34
	ds_read_b128 v[20:23], v3 offset:1920
	ds_read_b32 v32, v19 offset:30720
	ds_read_b128 v[24:27], v3 offset:1936
	ds_read_b32 v33, v19 offset:30976
	ds_read_b128 v[28:31], v3 offset:1952
	ds_read_b32 v34, v19 offset:31232
	s_waitcnt lgkmcnt(10)
	v_fmac_f32_e32 v4, v36, v48
	v_fmac_f32_e32 v5, v37, v48
	v_fmac_f32_e32 v6, v38, v48
	v_fmac_f32_e32 v8, v39, v48
	s_waitcnt lgkmcnt(8)
	v_fmac_f32_e32 v4, v40, v49
	v_fmac_f32_e32 v5, v41, v49
	v_fmac_f32_e32 v6, v42, v49
	v_fmac_f32_e32 v8, v43, v49
	s_waitcnt lgkmcnt(6)
	v_fmac_f32_e32 v4, v44, v50
	v_fmac_f32_e32 v5, v45, v50
	v_fmac_f32_e32 v6, v46, v50
	v_fmac_f32_e32 v8, v47, v50
	ds_read_b128 v[36:39], v3 offset:1968
	ds_read_b32 v48, v19 offset:31488
	ds_read_b128 v[40:43], v3 offset:1984
	ds_read_b32 v49, v19 offset:31744
	ds_read_b128 v[44:47], v3 offset:2000
	ds_read_b32 v50, v19 offset:32000
	s_waitcnt lgkmcnt(10)
	v_fmac_f32_e32 v4, v20, v32
	v_fmac_f32_e32 v5, v21, v32
	v_fmac_f32_e32 v6, v22, v32
	v_fmac_f32_e32 v8, v23, v32
	s_waitcnt lgkmcnt(8)
	v_fmac_f32_e32 v4, v24, v33
	v_fmac_f32_e32 v5, v25, v33
	v_fmac_f32_e32 v6, v26, v33
	v_fmac_f32_e32 v8, v27, v33
	s_waitcnt lgkmcnt(6)
	v_fmac_f32_e32 v4, v28, v34
	v_fmac_f32_e32 v5, v29, v34
	v_fmac_f32_e32 v6, v30, v34
	v_fmac_f32_e32 v8, v31, v34
	ds_read_b128 v[20:23], v3 offset:2016
	ds_read_b32 v32, v19 offset:32256
	ds_read_b128 v[24:27], v3 offset:2032
	ds_read_b32 v33, v19 offset:32512
	ds_read_b128 v[28:31], v3 offset:2048
	ds_read_b32 v34, v19 offset:32768
	s_waitcnt lgkmcnt(10)
	v_fmac_f32_e32 v4, v36, v48
	v_fmac_f32_e32 v5, v37, v48
	v_fmac_f32_e32 v6, v38, v48
	v_fmac_f32_e32 v8, v39, v48
	s_waitcnt lgkmcnt(8)
	v_fmac_f32_e32 v4, v40, v49
	v_fmac_f32_e32 v5, v41, v49
	v_fmac_f32_e32 v6, v42, v49
	v_fmac_f32_e32 v8, v43, v49
	s_waitcnt lgkmcnt(6)
	v_fmac_f32_e32 v4, v44, v50
	v_fmac_f32_e32 v5, v45, v50
	v_fmac_f32_e32 v6, v46, v50
	v_fmac_f32_e32 v8, v47, v50
	ds_read_b128 v[36:39], v3 offset:2064
	ds_read_b32 v48, v19 offset:33024
	ds_read_b128 v[40:43], v3 offset:2080
	ds_read_b32 v49, v19 offset:33280
	ds_read_b128 v[44:47], v3 offset:2096
	ds_read_b32 v50, v19 offset:33536
	s_waitcnt lgkmcnt(10)
	v_fmac_f32_e32 v4, v20, v32
	v_fmac_f32_e32 v5, v21, v32
	v_fmac_f32_e32 v6, v22, v32
	v_fmac_f32_e32 v8, v23, v32
	s_waitcnt lgkmcnt(8)
	v_fmac_f32_e32 v4, v24, v33
	v_fmac_f32_e32 v5, v25, v33
	v_fmac_f32_e32 v6, v26, v33
	v_fmac_f32_e32 v8, v27, v33
	s_waitcnt lgkmcnt(6)
	v_fmac_f32_e32 v4, v28, v34
	v_fmac_f32_e32 v5, v29, v34
	v_fmac_f32_e32 v6, v30, v34
	v_fmac_f32_e32 v8, v31, v34
	s_waitcnt lgkmcnt(4)
	v_fmac_f32_e32 v4, v36, v48
	v_fmac_f32_e32 v5, v37, v48
	v_fmac_f32_e32 v6, v38, v48
	v_fmac_f32_e32 v8, v39, v48
	s_waitcnt lgkmcnt(2)
	v_fmac_f32_e32 v4, v40, v49
	v_fmac_f32_e32 v5, v41, v49
	v_fmac_f32_e32 v6, v42, v49
	v_fmac_f32_e32 v8, v43, v49
	s_waitcnt lgkmcnt(0)
	v_fmac_f32_e32 v4, v44, v50
	v_fmac_f32_e32 v5, v45, v50
	v_fmac_f32_e32 v6, v46, v50
	v_fmac_f32_e32 v8, v47, v50
	s_add_u32 s42, s10, 0xd680000
	s_addc_u32 s43, s11, 0
	v_cvt_pk_bf16_f32 v4, v4, v4
	v_cvt_pk_bf16_f32 v5, v5, v5
	v_cvt_pk_bf16_f32 v6, v6, v6
	v_cvt_pk_bf16_f32 v8, v8, v8
	s_nop 0
	global_store_short v11, v4, s[42:43]
	global_store_short v11, v5, s[42:43] offset:2048
	global_store_short v12, v6, s[42:43]
	global_store_short v12, v8, s[42:43] offset:2048
